# nt hint on P0's read-once f32 w_ada loads (modulation GEMV weight stream)
# speedup vs baseline: 1.0105x; 1.0046x over previous
.LBB0_47:
	s_waitcnt vmcnt(0)
	s_mov_b32 vcc_lo, 0xaaaaaaaa
	s_mov_b32 vcc_hi, 0xaaaaaaaa
	v_readfirstlane_b32 s100, v60
	v_readfirstlane_b32 s101, v61
	v_and_b32_e32 v24, 1, v227
	v_lshrrev_b32_e32 v25, 4, v227
	v_lshl_add_u32 v25, v25, 3, v24
	v_mul_u32_u24_e32 v65, 0x6000, v25
	v_and_b32_e32 v24, 14, v227
	v_lshl_add_u32 v65, v24, 2, v65
	s_sub_u32 s100, s100, 0x56a000
	s_subb_u32 s101, s101, 0
	v_add_u32_e32 v122, v64, v1
	v_add_u32_e32 v123, 0x11220, v122
	v_add_u32_e32 v28, v63, v1
	v_add_u32_e32 v29, 0x11220, v28
	ds_read_b128 v[198:201], v122
	ds_read_b128 v[202:205], v123
	ds_read_b128 v[206:209], v122 offset:33024
	ds_read_b128 v[210:213], v123 offset:33024
	ds_read_b128 v[214:217], v28
	ds_read_b128 v[218:221], v29
	global_load_dwordx2 v[66:67], v65, s[100:101] nt
	s_add_u32 s100, s100, 0xc000
	s_addc_u32 s101, s101, 0
	global_load_dwordx2 v[68:69], v65, s[100:101] nt
	s_add_u32 s100, s100, 0xc000
	s_addc_u32 s101, s101, 0
	global_load_dwordx2 v[70:71], v65, s[100:101] nt
	s_add_u32 s100, s100, 0xc000
	s_addc_u32 s101, s101, 0
	global_load_dwordx2 v[72:73], v65, s[100:101] nt
	s_add_u32 s100, s100, 0x9c000
	s_addc_u32 s101, s101, 0
	global_load_dwordx2 v[74:75], v65, s[100:101] nt
	s_add_u32 s100, s100, 0xc000
	s_addc_u32 s101, s101, 0
	global_load_dwordx2 v[76:77], v65, s[100:101] nt
	s_add_u32 s100, s100, 0xc000
	s_addc_u32 s101, s101, 0
	global_load_dwordx2 v[78:79], v65, s[100:101] nt
	s_add_u32 s100, s100, 0xc000
	s_addc_u32 s101, s101, 0
	global_load_dwordx2 v[80:81], v65, s[100:101] nt
	s_add_u32 s100, s100, 0x9c000
	s_addc_u32 s101, s101, 0
	global_load_dwordx2 v[82:83], v65, s[100:101] nt
	s_add_u32 s100, s100, 0xc000
	s_addc_u32 s101, s101, 0
	global_load_dwordx2 v[84:85], v65, s[100:101] nt
	s_add_u32 s100, s100, 0xc000
	s_addc_u32 s101, s101, 0
	global_load_dwordx2 v[86:87], v65, s[100:101] nt
	s_add_u32 s100, s100, 0xc000
	s_addc_u32 s101, s101, 0
	global_load_dwordx2 v[88:89], v65, s[100:101] nt
	s_add_u32 s100, s100, 0x9c000
	s_addc_u32 s101, s101, 0
	global_load_dwordx2 v[90:91], v65, s[100:101] nt
	s_add_u32 s100, s100, 0xc000
	s_addc_u32 s101, s101, 0
	global_load_dwordx2 v[92:93], v65, s[100:101] nt
	s_add_u32 s100, s100, 0xc000
	s_addc_u32 s101, s101, 0
	global_load_dwordx2 v[94:95], v65, s[100:101] nt
	s_add_u32 s100, s100, 0xc000
	s_addc_u32 s101, s101, 0
	global_load_dwordx2 v[96:97], v65, s[100:101] nt
	s_add_u32 s100, s100, 0x9c000
	s_addc_u32 s101, s101, 0
	global_load_dwordx2 v[98:99], v65, s[100:101] nt
	s_add_u32 s100, s100, 0xc000
	s_addc_u32 s101, s101, 0
	global_load_dwordx2 v[100:101], v65, s[100:101] nt
	s_add_u32 s100, s100, 0xc000
	s_addc_u32 s101, s101, 0
	global_load_dwordx2 v[102:103], v65, s[100:101] nt
	s_add_u32 s100, s100, 0xc000
	s_addc_u32 s101, s101, 0
	global_load_dwordx2 v[104:105], v65, s[100:101] nt
	s_add_u32 s100, s100, 0x9c000
	s_addc_u32 s101, s101, 0
	global_load_dwordx2 v[106:107], v65, s[100:101] nt
	s_add_u32 s100, s100, 0xc000
	s_addc_u32 s101, s101, 0
	global_load_dwordx2 v[108:109], v65, s[100:101] nt
	s_add_u32 s100, s100, 0xc000
	s_addc_u32 s101, s101, 0
	global_load_dwordx2 v[110:111], v65, s[100:101] nt
	s_add_u32 s100, s100, 0xc000
	s_addc_u32 s101, s101, 0
	global_load_dwordx2 v[112:113], v65, s[100:101] nt
	s_add_u32 s100, s100, 0x9c000
	s_addc_u32 s101, s101, 0
	global_load_dwordx2 v[114:115], v65, s[100:101] nt
	s_add_u32 s100, s100, 0xc000
	s_addc_u32 s101, s101, 0
	global_load_dwordx2 v[116:117], v65, s[100:101] nt
	s_add_u32 s100, s100, 0xc000
	s_addc_u32 s101, s101, 0
	global_load_dwordx2 v[118:119], v65, s[100:101] nt
	s_add_u32 s100, s100, 0xc000
	s_addc_u32 s101, s101, 0
	global_load_dwordx2 v[120:121], v65, s[100:101] nt
	s_add_u32 s100, s100, 0x9c000
	s_addc_u32 s101, s101, 0
	global_load_dwordx2 v[126:127], v65, s[100:101] nt
	s_add_u32 s100, s100, 0xc000
	s_addc_u32 s101, s101, 0
	global_load_dwordx2 v[128:129], v65, s[100:101] nt
	s_add_u32 s100, s100, 0xc000
	s_addc_u32 s101, s101, 0
	global_load_dwordx2 v[130:131], v65, s[100:101] nt
	s_add_u32 s100, s100, 0xc000
	s_addc_u32 s101, s101, 0
	global_load_dwordx2 v[132:133], v65, s[100:101] nt
	s_add_u32 s100, s100, 0x9c000
	s_addc_u32 s101, s101, 0
	global_load_dwordx2 v[134:135], v65, s[100:101] nt
	s_add_u32 s100, s100, 0xc000
	s_addc_u32 s101, s101, 0
	global_load_dwordx2 v[136:137], v65, s[100:101] nt
	s_add_u32 s100, s100, 0xc000
	s_addc_u32 s101, s101, 0
	global_load_dwordx2 v[138:139], v65, s[100:101] nt
	s_add_u32 s100, s100, 0xc000
	s_addc_u32 s101, s101, 0
	global_load_dwordx2 v[140:141], v65, s[100:101] nt
	s_add_u32 s100, s100, 0x9c000
	s_addc_u32 s101, s101, 0
	global_load_dwordx2 v[142:143], v65, s[100:101] nt
	s_add_u32 s100, s100, 0xc000
	s_addc_u32 s101, s101, 0
	global_load_dwordx2 v[144:145], v65, s[100:101] nt
	s_add_u32 s100, s100, 0xc000
	s_addc_u32 s101, s101, 0
	global_load_dwordx2 v[146:147], v65, s[100:101] nt
	s_add_u32 s100, s100, 0xc000
	s_addc_u32 s101, s101, 0
	global_load_dwordx2 v[148:149], v65, s[100:101] nt
	s_add_u32 s100, s100, 0x9c000
	s_addc_u32 s101, s101, 0
	global_load_dwordx2 v[150:151], v65, s[100:101] nt
	s_add_u32 s100, s100, 0xc000
	s_addc_u32 s101, s101, 0
	global_load_dwordx2 v[152:153], v65, s[100:101] nt
	s_add_u32 s100, s100, 0xc000
	s_addc_u32 s101, s101, 0
	global_load_dwordx2 v[154:155], v65, s[100:101] nt
	s_add_u32 s100, s100, 0xc000
	s_addc_u32 s101, s101, 0
	global_load_dwordx2 v[156:157], v65, s[100:101] nt
	s_add_u32 s100, s100, 0x9c000
	s_addc_u32 s101, s101, 0
	global_load_dwordx2 v[158:159], v65, s[100:101] nt
	s_add_u32 s100, s100, 0xc000
	s_addc_u32 s101, s101, 0
	global_load_dwordx2 v[160:161], v65, s[100:101] nt
	s_add_u32 s100, s100, 0xc000
	s_addc_u32 s101, s101, 0
	global_load_dwordx2 v[162:163], v65, s[100:101] nt
	s_add_u32 s100, s100, 0xc000
	s_addc_u32 s101, s101, 0
	global_load_dwordx2 v[164:165], v65, s[100:101] nt
	s_add_u32 s100, s100, 0x9c000
	s_addc_u32 s101, s101, 0
	global_load_dwordx2 v[166:167], v65, s[100:101] nt
	s_add_u32 s100, s100, 0xc000
	s_addc_u32 s101, s101, 0
	global_load_dwordx2 v[168:169], v65, s[100:101] nt
	s_add_u32 s100, s100, 0xc000
	s_addc_u32 s101, s101, 0
	global_load_dwordx2 v[170:171], v65, s[100:101] nt
	s_add_u32 s100, s100, 0xc000
	s_addc_u32 s101, s101, 0
	global_load_dwordx2 v[172:173], v65, s[100:101] nt
	s_add_u32 s100, s100, 0x9c000
	s_addc_u32 s101, s101, 0
	global_load_dwordx2 v[174:175], v65, s[100:101] nt
	s_add_u32 s100, s100, 0xc000
	s_addc_u32 s101, s101, 0
	global_load_dwordx2 v[176:177], v65, s[100:101] nt
	s_add_u32 s100, s100, 0xc000
	s_addc_u32 s101, s101, 0
	global_load_dwordx2 v[178:179], v65, s[100:101] nt
	s_add_u32 s100, s100, 0xc000
	s_addc_u32 s101, s101, 0
	global_load_dwordx2 v[180:181], v65, s[100:101] nt
	s_add_u32 s100, s100, 0x9c000
	s_addc_u32 s101, s101, 0
	global_load_dwordx2 v[182:183], v65, s[100:101] nt
	s_add_u32 s100, s100, 0xc000
	s_addc_u32 s101, s101, 0
	global_load_dwordx2 v[184:185], v65, s[100:101] nt
	s_add_u32 s100, s100, 0xc000
	s_addc_u32 s101, s101, 0
	global_load_dwordx2 v[186:187], v65, s[100:101] nt
	s_add_u32 s100, s100, 0xc000
	s_addc_u32 s101, s101, 0
	global_load_dwordx2 v[188:189], v65, s[100:101] nt
	s_add_u32 s100, s100, 0x9c000
	s_addc_u32 s101, s101, 0
	global_load_dwordx2 v[190:191], v65, s[100:101] nt
	s_add_u32 s100, s100, 0xc000
	s_addc_u32 s101, s101, 0
	global_load_dwordx2 v[192:193], v65, s[100:101] nt
	s_add_u32 s100, s100, 0xc000
	s_addc_u32 s101, s101, 0
	global_load_dwordx2 v[194:195], v65, s[100:101] nt
	s_add_u32 s100, s100, 0xc000
	s_addc_u32 s101, s101, 0
	global_load_dwordx2 v[196:197], v65, s[100:101] nt
	s_add_u32 s100, s100, 0x9c000
	s_addc_u32 s101, s101, 0
	s_waitcnt vmcnt(60)
	v_cndmask_b32_e64 v24, v67, v66, vcc
	v_cndmask_b32_e64 v25, v69, v68, vcc
	v_cndmask_b32_e64 v26, v71, v70, vcc
	v_cndmask_b32_e64 v27, v73, v72, vcc
	v_mov_b32_dpp v222, v24 quad_perm:[1,0,3,2] row_mask:0xf bank_mask:0xf
	v_mov_b32_dpp v223, v25 quad_perm:[1,0,3,2] row_mask:0xf bank_mask:0xf
	v_mov_b32_dpp v224, v26 quad_perm:[1,0,3,2] row_mask:0xf bank_mask:0xf
	v_mov_b32_dpp v225, v27 quad_perm:[1,0,3,2] row_mask:0xf bank_mask:0xf
	v_cndmask_b32_e64 v66, v66, v222, vcc
	v_cndmask_b32_e64 v67, v222, v67, vcc
	v_cndmask_b32_e64 v68, v68, v223, vcc
	v_cndmask_b32_e64 v69, v223, v69, vcc
	v_cndmask_b32_e64 v70, v70, v224, vcc
	v_cndmask_b32_e64 v71, v224, v71, vcc
	v_cndmask_b32_e64 v72, v72, v225, vcc
	v_cndmask_b32_e64 v73, v225, v73, vcc
	v_cvt_pk_bf16_f32 v14, v66, v67
	v_cvt_pk_bf16_f32 v15, v68, v69
	v_cvt_pk_bf16_f32 v16, v70, v71
	v_cvt_pk_bf16_f32 v17, v72, v73
	v_lshlrev_b32_e32 v22, 16, v14
	v_and_b32_e32 v23, 0xffff0000, v14
	v_sub_f32_e32 v66, v66, v22
	v_sub_f32_e32 v67, v67, v23
	v_cvt_pk_bf16_f32 v18, v66, v67
	v_lshlrev_b32_e32 v22, 16, v15
	v_and_b32_e32 v23, 0xffff0000, v15
	v_sub_f32_e32 v68, v68, v22
	v_sub_f32_e32 v69, v69, v23
	v_cvt_pk_bf16_f32 v19, v68, v69
	v_lshlrev_b32_e32 v22, 16, v16
	v_and_b32_e32 v23, 0xffff0000, v16
	v_sub_f32_e32 v70, v70, v22
	v_sub_f32_e32 v71, v71, v23
	v_cvt_pk_bf16_f32 v20, v70, v71
	v_lshlrev_b32_e32 v22, 16, v17
	v_and_b32_e32 v23, 0xffff0000, v17
	v_sub_f32_e32 v72, v72, v22
	v_sub_f32_e32 v73, v73, v23
	v_cvt_pk_bf16_f32 v21, v72, v73
	global_load_dwordx2 v[66:67], v65, s[100:101] nt
	s_add_u32 s100, s100, 0xc000
	s_addc_u32 s101, s101, 0
	global_load_dwordx2 v[68:69], v65, s[100:101] nt
	s_add_u32 s100, s100, 0xc000
	s_addc_u32 s101, s101, 0
	global_load_dwordx2 v[70:71], v65, s[100:101] nt
	s_add_u32 s100, s100, 0xc000
	s_addc_u32 s101, s101, 0
	global_load_dwordx2 v[72:73], v65, s[100:101] nt
	s_add_u32 s100, s100, 0x9c000
	s_addc_u32 s101, s101, 0
	s_waitcnt lgkmcnt(0)
	v_mfma_f32_16x16x32_bf16 v[10:13], v[198:201], v[14:17], v[10:13]
	v_mfma_f32_16x16x32_bf16 v[6:9], v[206:209], v[14:17], v[6:9]
	v_mfma_f32_16x16x32_bf16 v[2:5], v[214:217], v[14:17], v[2:5]
	v_mfma_f32_16x16x32_bf16 v[10:13], v[198:201], v[18:21], v[10:13]
	ds_read_b128 v[198:201], v122 offset:64
	v_mfma_f32_16x16x32_bf16 v[6:9], v[206:209], v[18:21], v[6:9]
	ds_read_b128 v[206:209], v122 offset:33088
	v_mfma_f32_16x16x32_bf16 v[2:5], v[214:217], v[18:21], v[2:5]
	ds_read_b128 v[214:217], v28 offset:64
	v_mfma_f32_16x16x32_bf16 v[10:13], v[202:205], v[14:17], v[10:13]
	ds_read_b128 v[202:205], v123 offset:64
	v_mfma_f32_16x16x32_bf16 v[6:9], v[210:213], v[14:17], v[6:9]
	ds_read_b128 v[210:213], v123 offset:33088
	v_mfma_f32_16x16x32_bf16 v[2:5], v[218:221], v[14:17], v[2:5]
	ds_read_b128 v[218:221], v29 offset:64
	s_waitcnt vmcnt(60)
	v_cndmask_b32_e64 v24, v75, v74, vcc
	v_cndmask_b32_e64 v25, v77, v76, vcc
	v_cndmask_b32_e64 v26, v79, v78, vcc
	v_cndmask_b32_e64 v27, v81, v80, vcc
	v_mov_b32_dpp v222, v24 quad_perm:[1,0,3,2] row_mask:0xf bank_mask:0xf
	v_mov_b32_dpp v223, v25 quad_perm:[1,0,3,2] row_mask:0xf bank_mask:0xf
	v_mov_b32_dpp v224, v26 quad_perm:[1,0,3,2] row_mask:0xf bank_mask:0xf
	v_mov_b32_dpp v225, v27 quad_perm:[1,0,3,2] row_mask:0xf bank_mask:0xf
	v_cndmask_b32_e64 v74, v74, v222, vcc
	v_cndmask_b32_e64 v75, v222, v75, vcc
	v_cndmask_b32_e64 v76, v76, v223, vcc
	v_cndmask_b32_e64 v77, v223, v77, vcc
	v_cndmask_b32_e64 v78, v78, v224, vcc
	v_cndmask_b32_e64 v79, v224, v79, vcc
	v_cndmask_b32_e64 v80, v80, v225, vcc
	v_cndmask_b32_e64 v81, v225, v81, vcc
	v_cvt_pk_bf16_f32 v14, v74, v75
	v_cvt_pk_bf16_f32 v15, v76, v77
	v_cvt_pk_bf16_f32 v16, v78, v79
	v_cvt_pk_bf16_f32 v17, v80, v81
	v_lshlrev_b32_e32 v22, 16, v14
	v_and_b32_e32 v23, 0xffff0000, v14
	v_sub_f32_e32 v74, v74, v22
	v_sub_f32_e32 v75, v75, v23
	v_cvt_pk_bf16_f32 v18, v74, v75
	v_lshlrev_b32_e32 v22, 16, v15
	v_and_b32_e32 v23, 0xffff0000, v15
	v_sub_f32_e32 v76, v76, v22
	v_sub_f32_e32 v77, v77, v23
	v_cvt_pk_bf16_f32 v19, v76, v77
	v_lshlrev_b32_e32 v22, 16, v16
	v_and_b32_e32 v23, 0xffff0000, v16
	v_sub_f32_e32 v78, v78, v22
	v_sub_f32_e32 v79, v79, v23
	v_cvt_pk_bf16_f32 v20, v78, v79
	v_lshlrev_b32_e32 v22, 16, v17
	v_and_b32_e32 v23, 0xffff0000, v17
	v_sub_f32_e32 v80, v80, v22
	v_sub_f32_e32 v81, v81, v23
	v_cvt_pk_bf16_f32 v21, v80, v81
	global_load_dwordx2 v[74:75], v65, s[100:101] nt
	s_add_u32 s100, s100, 0xc000
	s_addc_u32 s101, s101, 0
	global_load_dwordx2 v[76:77], v65, s[100:101] nt
	s_add_u32 s100, s100, 0xc000
	s_addc_u32 s101, s101, 0
	global_load_dwordx2 v[78:79], v65, s[100:101] nt
	s_add_u32 s100, s100, 0xc000
	s_addc_u32 s101, s101, 0
	global_load_dwordx2 v[80:81], v65, s[100:101] nt
	s_add_u32 s100, s100, 0x9c000
	s_addc_u32 s101, s101, 0
	s_waitcnt lgkmcnt(0)
	v_mfma_f32_16x16x32_bf16 v[10:13], v[198:201], v[14:17], v[10:13]
	v_mfma_f32_16x16x32_bf16 v[6:9], v[206:209], v[14:17], v[6:9]
	v_mfma_f32_16x16x32_bf16 v[2:5], v[214:217], v[14:17], v[2:5]
	v_mfma_f32_16x16x32_bf16 v[10:13], v[198:201], v[18:21], v[10:13]
	ds_read_b128 v[198:201], v122 offset:128
	v_mfma_f32_16x16x32_bf16 v[6:9], v[206:209], v[18:21], v[6:9]
	ds_read_b128 v[206:209], v122 offset:33152
	v_mfma_f32_16x16x32_bf16 v[2:5], v[214:217], v[18:21], v[2:5]
	ds_read_b128 v[214:217], v28 offset:128
	v_mfma_f32_16x16x32_bf16 v[10:13], v[202:205], v[14:17], v[10:13]
	ds_read_b128 v[202:205], v123 offset:128
	v_mfma_f32_16x16x32_bf16 v[6:9], v[210:213], v[14:17], v[6:9]
	ds_read_b128 v[210:213], v123 offset:33152
	v_mfma_f32_16x16x32_bf16 v[2:5], v[218:221], v[14:17], v[2:5]
	ds_read_b128 v[218:221], v29 offset:128
	s_waitcnt vmcnt(60)
	v_cndmask_b32_e64 v24, v83, v82, vcc
	v_cndmask_b32_e64 v25, v85, v84, vcc
	v_cndmask_b32_e64 v26, v87, v86, vcc
	v_cndmask_b32_e64 v27, v89, v88, vcc
	v_mov_b32_dpp v222, v24 quad_perm:[1,0,3,2] row_mask:0xf bank_mask:0xf
	v_mov_b32_dpp v223, v25 quad_perm:[1,0,3,2] row_mask:0xf bank_mask:0xf
	v_mov_b32_dpp v224, v26 quad_perm:[1,0,3,2] row_mask:0xf bank_mask:0xf
	v_mov_b32_dpp v225, v27 quad_perm:[1,0,3,2] row_mask:0xf bank_mask:0xf
	v_cndmask_b32_e64 v82, v82, v222, vcc
	v_cndmask_b32_e64 v83, v222, v83, vcc
	v_cndmask_b32_e64 v84, v84, v223, vcc
	v_cndmask_b32_e64 v85, v223, v85, vcc
	v_cndmask_b32_e64 v86, v86, v224, vcc
	v_cndmask_b32_e64 v87, v224, v87, vcc
	v_cndmask_b32_e64 v88, v88, v225, vcc
	v_cndmask_b32_e64 v89, v225, v89, vcc
	v_cvt_pk_bf16_f32 v14, v82, v83
	v_cvt_pk_bf16_f32 v15, v84, v85
	v_cvt_pk_bf16_f32 v16, v86, v87
	v_cvt_pk_bf16_f32 v17, v88, v89
	v_lshlrev_b32_e32 v22, 16, v14
	v_and_b32_e32 v23, 0xffff0000, v14
	v_sub_f32_e32 v82, v82, v22
	v_sub_f32_e32 v83, v83, v23
	v_cvt_pk_bf16_f32 v18, v82, v83
	v_lshlrev_b32_e32 v22, 16, v15
	v_and_b32_e32 v23, 0xffff0000, v15
	v_sub_f32_e32 v84, v84, v22
	v_sub_f32_e32 v85, v85, v23
	v_cvt_pk_bf16_f32 v19, v84, v85
	v_lshlrev_b32_e32 v22, 16, v16
	v_and_b32_e32 v23, 0xffff0000, v16
	v_sub_f32_e32 v86, v86, v22
	v_sub_f32_e32 v87, v87, v23
	v_cvt_pk_bf16_f32 v20, v86, v87
	v_lshlrev_b32_e32 v22, 16, v17
	v_and_b32_e32 v23, 0xffff0000, v17
	v_sub_f32_e32 v88, v88, v22
	v_sub_f32_e32 v89, v89, v23
	v_cvt_pk_bf16_f32 v21, v88, v89
	global_load_dwordx2 v[82:83], v65, s[100:101] nt
	s_add_u32 s100, s100, 0xc000
	s_addc_u32 s101, s101, 0
	global_load_dwordx2 v[84:85], v65, s[100:101] nt
	s_add_u32 s100, s100, 0xc000
	s_addc_u32 s101, s101, 0
	global_load_dwordx2 v[86:87], v65, s[100:101] nt
	s_add_u32 s100, s100, 0xc000
	s_addc_u32 s101, s101, 0
	global_load_dwordx2 v[88:89], v65, s[100:101] nt
	s_add_u32 s100, s100, 0x9c000
	s_addc_u32 s101, s101, 0
	s_waitcnt lgkmcnt(0)
	v_mfma_f32_16x16x32_bf16 v[10:13], v[198:201], v[14:17], v[10:13]
	v_mfma_f32_16x16x32_bf16 v[6:9], v[206:209], v[14:17], v[6:9]
	v_mfma_f32_16x16x32_bf16 v[2:5], v[214:217], v[14:17], v[2:5]
	v_mfma_f32_16x16x32_bf16 v[10:13], v[198:201], v[18:21], v[10:13]
	ds_read_b128 v[198:201], v122 offset:192
	v_mfma_f32_16x16x32_bf16 v[6:9], v[206:209], v[18:21], v[6:9]
	ds_read_b128 v[206:209], v122 offset:33216
	v_mfma_f32_16x16x32_bf16 v[2:5], v[214:217], v[18:21], v[2:5]
	ds_read_b128 v[214:217], v28 offset:192
	v_mfma_f32_16x16x32_bf16 v[10:13], v[202:205], v[14:17], v[10:13]
	ds_read_b128 v[202:205], v123 offset:192
	v_mfma_f32_16x16x32_bf16 v[6:9], v[210:213], v[14:17], v[6:9]
	ds_read_b128 v[210:213], v123 offset:33216
	v_mfma_f32_16x16x32_bf16 v[2:5], v[218:221], v[14:17], v[2:5]
	ds_read_b128 v[218:221], v29 offset:192
	s_waitcnt vmcnt(60)
	v_cndmask_b32_e64 v24, v91, v90, vcc
	v_cndmask_b32_e64 v25, v93, v92, vcc
	v_cndmask_b32_e64 v26, v95, v94, vcc
	v_cndmask_b32_e64 v27, v97, v96, vcc
	v_mov_b32_dpp v222, v24 quad_perm:[1,0,3,2] row_mask:0xf bank_mask:0xf
	v_mov_b32_dpp v223, v25 quad_perm:[1,0,3,2] row_mask:0xf bank_mask:0xf
	v_mov_b32_dpp v224, v26 quad_perm:[1,0,3,2] row_mask:0xf bank_mask:0xf
	v_mov_b32_dpp v225, v27 quad_perm:[1,0,3,2] row_mask:0xf bank_mask:0xf
	v_cndmask_b32_e64 v90, v90, v222, vcc
	v_cndmask_b32_e64 v91, v222, v91, vcc
	v_cndmask_b32_e64 v92, v92, v223, vcc
	v_cndmask_b32_e64 v93, v223, v93, vcc
	v_cndmask_b32_e64 v94, v94, v224, vcc
	v_cndmask_b32_e64 v95, v224, v95, vcc
	v_cndmask_b32_e64 v96, v96, v225, vcc
	v_cndmask_b32_e64 v97, v225, v97, vcc
	v_cvt_pk_bf16_f32 v14, v90, v91
	v_cvt_pk_bf16_f32 v15, v92, v93
	v_cvt_pk_bf16_f32 v16, v94, v95
	v_cvt_pk_bf16_f32 v17, v96, v97
	v_lshlrev_b32_e32 v22, 16, v14
	v_and_b32_e32 v23, 0xffff0000, v14
	v_sub_f32_e32 v90, v90, v22
	v_sub_f32_e32 v91, v91, v23
	v_cvt_pk_bf16_f32 v18, v90, v91
	v_lshlrev_b32_e32 v22, 16, v15
	v_and_b32_e32 v23, 0xffff0000, v15
	v_sub_f32_e32 v92, v92, v22
	v_sub_f32_e32 v93, v93, v23
	v_cvt_pk_bf16_f32 v19, v92, v93
	v_lshlrev_b32_e32 v22, 16, v16
	v_and_b32_e32 v23, 0xffff0000, v16
	v_sub_f32_e32 v94, v94, v22
	v_sub_f32_e32 v95, v95, v23
	v_cvt_pk_bf16_f32 v20, v94, v95
	v_lshlrev_b32_e32 v22, 16, v17
	v_and_b32_e32 v23, 0xffff0000, v17
	v_sub_f32_e32 v96, v96, v22
	v_sub_f32_e32 v97, v97, v23
	v_cvt_pk_bf16_f32 v21, v96, v97
	global_load_dwordx2 v[90:91], v65, s[100:101] nt
	s_add_u32 s100, s100, 0xc000
	s_addc_u32 s101, s101, 0
	global_load_dwordx2 v[92:93], v65, s[100:101] nt
	s_add_u32 s100, s100, 0xc000
	s_addc_u32 s101, s101, 0
	global_load_dwordx2 v[94:95], v65, s[100:101] nt
	s_add_u32 s100, s100, 0xc000
	s_addc_u32 s101, s101, 0
	global_load_dwordx2 v[96:97], v65, s[100:101] nt
	s_add_u32 s100, s100, 0x9c000
	s_addc_u32 s101, s101, 0
	s_waitcnt lgkmcnt(0)
	v_mfma_f32_16x16x32_bf16 v[10:13], v[198:201], v[14:17], v[10:13]
	v_mfma_f32_16x16x32_bf16 v[6:9], v[206:209], v[14:17], v[6:9]
	v_mfma_f32_16x16x32_bf16 v[2:5], v[214:217], v[14:17], v[2:5]
	v_mfma_f32_16x16x32_bf16 v[10:13], v[198:201], v[18:21], v[10:13]
	ds_read_b128 v[198:201], v122 offset:256
	v_mfma_f32_16x16x32_bf16 v[6:9], v[206:209], v[18:21], v[6:9]
	ds_read_b128 v[206:209], v122 offset:33280
	v_mfma_f32_16x16x32_bf16 v[2:5], v[214:217], v[18:21], v[2:5]
	ds_read_b128 v[214:217], v28 offset:256
	v_mfma_f32_16x16x32_bf16 v[10:13], v[202:205], v[14:17], v[10:13]
	ds_read_b128 v[202:205], v123 offset:256
	v_mfma_f32_16x16x32_bf16 v[6:9], v[210:213], v[14:17], v[6:9]
	ds_read_b128 v[210:213], v123 offset:33280
	v_mfma_f32_16x16x32_bf16 v[2:5], v[218:221], v[14:17], v[2:5]
	ds_read_b128 v[218:221], v29 offset:256
	s_waitcnt vmcnt(60)
	v_cndmask_b32_e64 v24, v99, v98, vcc
	v_cndmask_b32_e64 v25, v101, v100, vcc
	v_cndmask_b32_e64 v26, v103, v102, vcc
	v_cndmask_b32_e64 v27, v105, v104, vcc
	v_mov_b32_dpp v222, v24 quad_perm:[1,0,3,2] row_mask:0xf bank_mask:0xf
	v_mov_b32_dpp v223, v25 quad_perm:[1,0,3,2] row_mask:0xf bank_mask:0xf
	v_mov_b32_dpp v224, v26 quad_perm:[1,0,3,2] row_mask:0xf bank_mask:0xf
	v_mov_b32_dpp v225, v27 quad_perm:[1,0,3,2] row_mask:0xf bank_mask:0xf
	v_cndmask_b32_e64 v98, v98, v222, vcc
	v_cndmask_b32_e64 v99, v222, v99, vcc
	v_cndmask_b32_e64 v100, v100, v223, vcc
	v_cndmask_b32_e64 v101, v223, v101, vcc
	v_cndmask_b32_e64 v102, v102, v224, vcc
	v_cndmask_b32_e64 v103, v224, v103, vcc
	v_cndmask_b32_e64 v104, v104, v225, vcc
	v_cndmask_b32_e64 v105, v225, v105, vcc
	v_cvt_pk_bf16_f32 v14, v98, v99
	v_cvt_pk_bf16_f32 v15, v100, v101
	v_cvt_pk_bf16_f32 v16, v102, v103
	v_cvt_pk_bf16_f32 v17, v104, v105
	v_lshlrev_b32_e32 v22, 16, v14
	v_and_b32_e32 v23, 0xffff0000, v14
	v_sub_f32_e32 v98, v98, v22
	v_sub_f32_e32 v99, v99, v23
	v_cvt_pk_bf16_f32 v18, v98, v99
	v_lshlrev_b32_e32 v22, 16, v15
	v_and_b32_e32 v23, 0xffff0000, v15
	v_sub_f32_e32 v100, v100, v22
	v_sub_f32_e32 v101, v101, v23
	v_cvt_pk_bf16_f32 v19, v100, v101
	v_lshlrev_b32_e32 v22, 16, v16
	v_and_b32_e32 v23, 0xffff0000, v16
	v_sub_f32_e32 v102, v102, v22
	v_sub_f32_e32 v103, v103, v23
	v_cvt_pk_bf16_f32 v20, v102, v103
	v_lshlrev_b32_e32 v22, 16, v17
	v_and_b32_e32 v23, 0xffff0000, v17
	v_sub_f32_e32 v104, v104, v22
	v_sub_f32_e32 v105, v105, v23
	v_cvt_pk_bf16_f32 v21, v104, v105
	global_load_dwordx2 v[98:99], v65, s[100:101] nt
	s_add_u32 s100, s100, 0xc000
	s_addc_u32 s101, s101, 0
	global_load_dwordx2 v[100:101], v65, s[100:101] nt
	s_add_u32 s100, s100, 0xc000
	s_addc_u32 s101, s101, 0
	global_load_dwordx2 v[102:103], v65, s[100:101] nt
	s_add_u32 s100, s100, 0xc000
	s_addc_u32 s101, s101, 0
	global_load_dwordx2 v[104:105], v65, s[100:101] nt
	s_add_u32 s100, s100, 0x9c000
	s_addc_u32 s101, s101, 0
	s_waitcnt lgkmcnt(0)
	v_mfma_f32_16x16x32_bf16 v[10:13], v[198:201], v[14:17], v[10:13]
	v_mfma_f32_16x16x32_bf16 v[6:9], v[206:209], v[14:17], v[6:9]
	v_mfma_f32_16x16x32_bf16 v[2:5], v[214:217], v[14:17], v[2:5]
	v_mfma_f32_16x16x32_bf16 v[10:13], v[198:201], v[18:21], v[10:13]
	ds_read_b128 v[198:201], v122 offset:320
	v_mfma_f32_16x16x32_bf16 v[6:9], v[206:209], v[18:21], v[6:9]
	ds_read_b128 v[206:209], v122 offset:33344
	v_mfma_f32_16x16x32_bf16 v[2:5], v[214:217], v[18:21], v[2:5]
	ds_read_b128 v[214:217], v28 offset:320
	v_mfma_f32_16x16x32_bf16 v[10:13], v[202:205], v[14:17], v[10:13]
	ds_read_b128 v[202:205], v123 offset:320
	v_mfma_f32_16x16x32_bf16 v[6:9], v[210:213], v[14:17], v[6:9]
	ds_read_b128 v[210:213], v123 offset:33344
	v_mfma_f32_16x16x32_bf16 v[2:5], v[218:221], v[14:17], v[2:5]
	ds_read_b128 v[218:221], v29 offset:320
	s_waitcnt vmcnt(60)
	v_cndmask_b32_e64 v24, v107, v106, vcc
	v_cndmask_b32_e64 v25, v109, v108, vcc
	v_cndmask_b32_e64 v26, v111, v110, vcc
	v_cndmask_b32_e64 v27, v113, v112, vcc
	v_mov_b32_dpp v222, v24 quad_perm:[1,0,3,2] row_mask:0xf bank_mask:0xf
	v_mov_b32_dpp v223, v25 quad_perm:[1,0,3,2] row_mask:0xf bank_mask:0xf
	v_mov_b32_dpp v224, v26 quad_perm:[1,0,3,2] row_mask:0xf bank_mask:0xf
	v_mov_b32_dpp v225, v27 quad_perm:[1,0,3,2] row_mask:0xf bank_mask:0xf
	v_cndmask_b32_e64 v106, v106, v222, vcc
	v_cndmask_b32_e64 v107, v222, v107, vcc
	v_cndmask_b32_e64 v108, v108, v223, vcc
	v_cndmask_b32_e64 v109, v223, v109, vcc
	v_cndmask_b32_e64 v110, v110, v224, vcc
	v_cndmask_b32_e64 v111, v224, v111, vcc
	v_cndmask_b32_e64 v112, v112, v225, vcc
	v_cndmask_b32_e64 v113, v225, v113, vcc
	v_cvt_pk_bf16_f32 v14, v106, v107
	v_cvt_pk_bf16_f32 v15, v108, v109
	v_cvt_pk_bf16_f32 v16, v110, v111
	v_cvt_pk_bf16_f32 v17, v112, v113
	v_lshlrev_b32_e32 v22, 16, v14
	v_and_b32_e32 v23, 0xffff0000, v14
	v_sub_f32_e32 v106, v106, v22
	v_sub_f32_e32 v107, v107, v23
	v_cvt_pk_bf16_f32 v18, v106, v107
	v_lshlrev_b32_e32 v22, 16, v15
	v_and_b32_e32 v23, 0xffff0000, v15
	v_sub_f32_e32 v108, v108, v22
	v_sub_f32_e32 v109, v109, v23
	v_cvt_pk_bf16_f32 v19, v108, v109
	v_lshlrev_b32_e32 v22, 16, v16
	v_and_b32_e32 v23, 0xffff0000, v16
	v_sub_f32_e32 v110, v110, v22
	v_sub_f32_e32 v111, v111, v23
	v_cvt_pk_bf16_f32 v20, v110, v111
	v_lshlrev_b32_e32 v22, 16, v17
	v_and_b32_e32 v23, 0xffff0000, v17
	v_sub_f32_e32 v112, v112, v22
	v_sub_f32_e32 v113, v113, v23
	v_cvt_pk_bf16_f32 v21, v112, v113
	global_load_dwordx2 v[106:107], v65, s[100:101] nt
	s_add_u32 s100, s100, 0xc000
	s_addc_u32 s101, s101, 0
	global_load_dwordx2 v[108:109], v65, s[100:101] nt
	s_add_u32 s100, s100, 0xc000
	s_addc_u32 s101, s101, 0
	global_load_dwordx2 v[110:111], v65, s[100:101] nt
	s_add_u32 s100, s100, 0xc000
	s_addc_u32 s101, s101, 0
	global_load_dwordx2 v[112:113], v65, s[100:101] nt
	s_add_u32 s100, s100, 0x9c000
	s_addc_u32 s101, s101, 0
	s_waitcnt lgkmcnt(0)
	v_mfma_f32_16x16x32_bf16 v[10:13], v[198:201], v[14:17], v[10:13]
	v_mfma_f32_16x16x32_bf16 v[6:9], v[206:209], v[14:17], v[6:9]
	v_mfma_f32_16x16x32_bf16 v[2:5], v[214:217], v[14:17], v[2:5]
	v_mfma_f32_16x16x32_bf16 v[10:13], v[198:201], v[18:21], v[10:13]
	ds_read_b128 v[198:201], v122 offset:384
	v_mfma_f32_16x16x32_bf16 v[6:9], v[206:209], v[18:21], v[6:9]
	ds_read_b128 v[206:209], v122 offset:33408
	v_mfma_f32_16x16x32_bf16 v[2:5], v[214:217], v[18:21], v[2:5]
	ds_read_b128 v[214:217], v28 offset:384
	v_mfma_f32_16x16x32_bf16 v[10:13], v[202:205], v[14:17], v[10:13]
	ds_read_b128 v[202:205], v123 offset:384
	v_mfma_f32_16x16x32_bf16 v[6:9], v[210:213], v[14:17], v[6:9]
	ds_read_b128 v[210:213], v123 offset:33408
	v_mfma_f32_16x16x32_bf16 v[2:5], v[218:221], v[14:17], v[2:5]
	ds_read_b128 v[218:221], v29 offset:384
	s_waitcnt vmcnt(60)
	v_cndmask_b32_e64 v24, v115, v114, vcc
	v_cndmask_b32_e64 v25, v117, v116, vcc
	v_cndmask_b32_e64 v26, v119, v118, vcc
	v_cndmask_b32_e64 v27, v121, v120, vcc
	v_mov_b32_dpp v222, v24 quad_perm:[1,0,3,2] row_mask:0xf bank_mask:0xf
	v_mov_b32_dpp v223, v25 quad_perm:[1,0,3,2] row_mask:0xf bank_mask:0xf
	v_mov_b32_dpp v224, v26 quad_perm:[1,0,3,2] row_mask:0xf bank_mask:0xf
	v_mov_b32_dpp v225, v27 quad_perm:[1,0,3,2] row_mask:0xf bank_mask:0xf
	v_cndmask_b32_e64 v114, v114, v222, vcc
	v_cndmask_b32_e64 v115, v222, v115, vcc
	v_cndmask_b32_e64 v116, v116, v223, vcc
	v_cndmask_b32_e64 v117, v223, v117, vcc
	v_cndmask_b32_e64 v118, v118, v224, vcc
	v_cndmask_b32_e64 v119, v224, v119, vcc
	v_cndmask_b32_e64 v120, v120, v225, vcc
	v_cndmask_b32_e64 v121, v225, v121, vcc
	v_cvt_pk_bf16_f32 v14, v114, v115
	v_cvt_pk_bf16_f32 v15, v116, v117
	v_cvt_pk_bf16_f32 v16, v118, v119
	v_cvt_pk_bf16_f32 v17, v120, v121
	v_lshlrev_b32_e32 v22, 16, v14
	v_and_b32_e32 v23, 0xffff0000, v14
	v_sub_f32_e32 v114, v114, v22
	v_sub_f32_e32 v115, v115, v23
	v_cvt_pk_bf16_f32 v18, v114, v115
	v_lshlrev_b32_e32 v22, 16, v15
	v_and_b32_e32 v23, 0xffff0000, v15
	v_sub_f32_e32 v116, v116, v22
	v_sub_f32_e32 v117, v117, v23
	v_cvt_pk_bf16_f32 v19, v116, v117
	v_lshlrev_b32_e32 v22, 16, v16
	v_and_b32_e32 v23, 0xffff0000, v16
	v_sub_f32_e32 v118, v118, v22
	v_sub_f32_e32 v119, v119, v23
	v_cvt_pk_bf16_f32 v20, v118, v119
	v_lshlrev_b32_e32 v22, 16, v17
	v_and_b32_e32 v23, 0xffff0000, v17
	v_sub_f32_e32 v120, v120, v22
	v_sub_f32_e32 v121, v121, v23
	v_cvt_pk_bf16_f32 v21, v120, v121
	global_load_dwordx2 v[114:115], v65, s[100:101] nt
	s_add_u32 s100, s100, 0xc000
	s_addc_u32 s101, s101, 0
	global_load_dwordx2 v[116:117], v65, s[100:101] nt
	s_add_u32 s100, s100, 0xc000
	s_addc_u32 s101, s101, 0
	global_load_dwordx2 v[118:119], v65, s[100:101] nt
	s_add_u32 s100, s100, 0xc000
	s_addc_u32 s101, s101, 0
	global_load_dwordx2 v[120:121], v65, s[100:101] nt
	s_add_u32 s100, s100, 0x9c000
	s_addc_u32 s101, s101, 0
	s_waitcnt lgkmcnt(0)
	v_mfma_f32_16x16x32_bf16 v[10:13], v[198:201], v[14:17], v[10:13]
	v_mfma_f32_16x16x32_bf16 v[6:9], v[206:209], v[14:17], v[6:9]
	v_mfma_f32_16x16x32_bf16 v[2:5], v[214:217], v[14:17], v[2:5]
	v_mfma_f32_16x16x32_bf16 v[10:13], v[198:201], v[18:21], v[10:13]
	ds_read_b128 v[198:201], v122 offset:448
	v_mfma_f32_16x16x32_bf16 v[6:9], v[206:209], v[18:21], v[6:9]
	ds_read_b128 v[206:209], v122 offset:33472
	v_mfma_f32_16x16x32_bf16 v[2:5], v[214:217], v[18:21], v[2:5]
	ds_read_b128 v[214:217], v28 offset:448
	v_mfma_f32_16x16x32_bf16 v[10:13], v[202:205], v[14:17], v[10:13]
	ds_read_b128 v[202:205], v123 offset:448
	v_mfma_f32_16x16x32_bf16 v[6:9], v[210:213], v[14:17], v[6:9]
	ds_read_b128 v[210:213], v123 offset:33472
	v_mfma_f32_16x16x32_bf16 v[2:5], v[218:221], v[14:17], v[2:5]
	ds_read_b128 v[218:221], v29 offset:448
	s_waitcnt vmcnt(60)
	v_cndmask_b32_e64 v24, v127, v126, vcc
	v_cndmask_b32_e64 v25, v129, v128, vcc
	v_cndmask_b32_e64 v26, v131, v130, vcc
	v_cndmask_b32_e64 v27, v133, v132, vcc
	v_mov_b32_dpp v222, v24 quad_perm:[1,0,3,2] row_mask:0xf bank_mask:0xf
	v_mov_b32_dpp v223, v25 quad_perm:[1,0,3,2] row_mask:0xf bank_mask:0xf
	v_mov_b32_dpp v224, v26 quad_perm:[1,0,3,2] row_mask:0xf bank_mask:0xf
	v_mov_b32_dpp v225, v27 quad_perm:[1,0,3,2] row_mask:0xf bank_mask:0xf
	v_cndmask_b32_e64 v126, v126, v222, vcc
	v_cndmask_b32_e64 v127, v222, v127, vcc
	v_cndmask_b32_e64 v128, v128, v223, vcc
	v_cndmask_b32_e64 v129, v223, v129, vcc
	v_cndmask_b32_e64 v130, v130, v224, vcc
	v_cndmask_b32_e64 v131, v224, v131, vcc
	v_cndmask_b32_e64 v132, v132, v225, vcc
	v_cndmask_b32_e64 v133, v225, v133, vcc
	v_cvt_pk_bf16_f32 v14, v126, v127
	v_cvt_pk_bf16_f32 v15, v128, v129
	v_cvt_pk_bf16_f32 v16, v130, v131
	v_cvt_pk_bf16_f32 v17, v132, v133
	v_lshlrev_b32_e32 v22, 16, v14
	v_and_b32_e32 v23, 0xffff0000, v14
	v_sub_f32_e32 v126, v126, v22
	v_sub_f32_e32 v127, v127, v23
	v_cvt_pk_bf16_f32 v18, v126, v127
	v_lshlrev_b32_e32 v22, 16, v15
	v_and_b32_e32 v23, 0xffff0000, v15
	v_sub_f32_e32 v128, v128, v22
	v_sub_f32_e32 v129, v129, v23
	v_cvt_pk_bf16_f32 v19, v128, v129
	v_lshlrev_b32_e32 v22, 16, v16
	v_and_b32_e32 v23, 0xffff0000, v16
	v_sub_f32_e32 v130, v130, v22
	v_sub_f32_e32 v131, v131, v23
	v_cvt_pk_bf16_f32 v20, v130, v131
	v_lshlrev_b32_e32 v22, 16, v17
	v_and_b32_e32 v23, 0xffff0000, v17
	v_sub_f32_e32 v132, v132, v22
	v_sub_f32_e32 v133, v133, v23
	v_cvt_pk_bf16_f32 v21, v132, v133
	global_load_dwordx2 v[126:127], v65, s[100:101] nt
	s_add_u32 s100, s100, 0xc000
	s_addc_u32 s101, s101, 0
	global_load_dwordx2 v[128:129], v65, s[100:101] nt
	s_add_u32 s100, s100, 0xc000
	s_addc_u32 s101, s101, 0
	global_load_dwordx2 v[130:131], v65, s[100:101] nt
	s_add_u32 s100, s100, 0xc000
	s_addc_u32 s101, s101, 0
	global_load_dwordx2 v[132:133], v65, s[100:101] nt
	s_add_u32 s100, s100, 0x9c000
	s_addc_u32 s101, s101, 0
	s_waitcnt lgkmcnt(0)
	v_mfma_f32_16x16x32_bf16 v[10:13], v[198:201], v[14:17], v[10:13]
	v_mfma_f32_16x16x32_bf16 v[6:9], v[206:209], v[14:17], v[6:9]
	v_mfma_f32_16x16x32_bf16 v[2:5], v[214:217], v[14:17], v[2:5]
	v_mfma_f32_16x16x32_bf16 v[10:13], v[198:201], v[18:21], v[10:13]
	ds_read_b128 v[198:201], v122 offset:512
	v_mfma_f32_16x16x32_bf16 v[6:9], v[206:209], v[18:21], v[6:9]
	ds_read_b128 v[206:209], v122 offset:33536
	v_mfma_f32_16x16x32_bf16 v[2:5], v[214:217], v[18:21], v[2:5]
	ds_read_b128 v[214:217], v28 offset:512
	v_mfma_f32_16x16x32_bf16 v[10:13], v[202:205], v[14:17], v[10:13]
	ds_read_b128 v[202:205], v123 offset:512
	v_mfma_f32_16x16x32_bf16 v[6:9], v[210:213], v[14:17], v[6:9]
	ds_read_b128 v[210:213], v123 offset:33536
	v_mfma_f32_16x16x32_bf16 v[2:5], v[218:221], v[14:17], v[2:5]
	ds_read_b128 v[218:221], v29 offset:512
	s_waitcnt vmcnt(60)
	v_cndmask_b32_e64 v24, v135, v134, vcc
	v_cndmask_b32_e64 v25, v137, v136, vcc
	v_cndmask_b32_e64 v26, v139, v138, vcc
	v_cndmask_b32_e64 v27, v141, v140, vcc
	v_mov_b32_dpp v222, v24 quad_perm:[1,0,3,2] row_mask:0xf bank_mask:0xf
	v_mov_b32_dpp v223, v25 quad_perm:[1,0,3,2] row_mask:0xf bank_mask:0xf
	v_mov_b32_dpp v224, v26 quad_perm:[1,0,3,2] row_mask:0xf bank_mask:0xf
	v_mov_b32_dpp v225, v27 quad_perm:[1,0,3,2] row_mask:0xf bank_mask:0xf
	v_cndmask_b32_e64 v134, v134, v222, vcc
	v_cndmask_b32_e64 v135, v222, v135, vcc
	v_cndmask_b32_e64 v136, v136, v223, vcc
	v_cndmask_b32_e64 v137, v223, v137, vcc
	v_cndmask_b32_e64 v138, v138, v224, vcc
	v_cndmask_b32_e64 v139, v224, v139, vcc
	v_cndmask_b32_e64 v140, v140, v225, vcc
	v_cndmask_b32_e64 v141, v225, v141, vcc
	v_cvt_pk_bf16_f32 v14, v134, v135
	v_cvt_pk_bf16_f32 v15, v136, v137
	v_cvt_pk_bf16_f32 v16, v138, v139
	v_cvt_pk_bf16_f32 v17, v140, v141
	v_lshlrev_b32_e32 v22, 16, v14
	v_and_b32_e32 v23, 0xffff0000, v14
	v_sub_f32_e32 v134, v134, v22
	v_sub_f32_e32 v135, v135, v23
	v_cvt_pk_bf16_f32 v18, v134, v135
	v_lshlrev_b32_e32 v22, 16, v15
	v_and_b32_e32 v23, 0xffff0000, v15
	v_sub_f32_e32 v136, v136, v22
	v_sub_f32_e32 v137, v137, v23
	v_cvt_pk_bf16_f32 v19, v136, v137
	v_lshlrev_b32_e32 v22, 16, v16
	v_and_b32_e32 v23, 0xffff0000, v16
	v_sub_f32_e32 v138, v138, v22
	v_sub_f32_e32 v139, v139, v23
	v_cvt_pk_bf16_f32 v20, v138, v139
	v_lshlrev_b32_e32 v22, 16, v17
	v_and_b32_e32 v23, 0xffff0000, v17
	v_sub_f32_e32 v140, v140, v22
	v_sub_f32_e32 v141, v141, v23
	v_cvt_pk_bf16_f32 v21, v140, v141
	global_load_dwordx2 v[134:135], v65, s[100:101] nt
	s_add_u32 s100, s100, 0xc000
	s_addc_u32 s101, s101, 0
	global_load_dwordx2 v[136:137], v65, s[100:101] nt
	s_add_u32 s100, s100, 0xc000
	s_addc_u32 s101, s101, 0
	global_load_dwordx2 v[138:139], v65, s[100:101] nt
	s_add_u32 s100, s100, 0xc000
	s_addc_u32 s101, s101, 0
	global_load_dwordx2 v[140:141], v65, s[100:101] nt
	s_add_u32 s100, s100, 0x9c000
	s_addc_u32 s101, s101, 0
	s_waitcnt lgkmcnt(0)
	v_mfma_f32_16x16x32_bf16 v[10:13], v[198:201], v[14:17], v[10:13]
	v_mfma_f32_16x16x32_bf16 v[6:9], v[206:209], v[14:17], v[6:9]
	v_mfma_f32_16x16x32_bf16 v[2:5], v[214:217], v[14:17], v[2:5]
	v_mfma_f32_16x16x32_bf16 v[10:13], v[198:201], v[18:21], v[10:13]
	ds_read_b128 v[198:201], v122 offset:576
	v_mfma_f32_16x16x32_bf16 v[6:9], v[206:209], v[18:21], v[6:9]
	ds_read_b128 v[206:209], v122 offset:33600
	v_mfma_f32_16x16x32_bf16 v[2:5], v[214:217], v[18:21], v[2:5]
	ds_read_b128 v[214:217], v28 offset:576
	v_mfma_f32_16x16x32_bf16 v[10:13], v[202:205], v[14:17], v[10:13]
	ds_read_b128 v[202:205], v123 offset:576
	v_mfma_f32_16x16x32_bf16 v[6:9], v[210:213], v[14:17], v[6:9]
	ds_read_b128 v[210:213], v123 offset:33600
	v_mfma_f32_16x16x32_bf16 v[2:5], v[218:221], v[14:17], v[2:5]
	ds_read_b128 v[218:221], v29 offset:576
	s_waitcnt vmcnt(60)
	v_cndmask_b32_e64 v24, v143, v142, vcc
	v_cndmask_b32_e64 v25, v145, v144, vcc
	v_cndmask_b32_e64 v26, v147, v146, vcc
	v_cndmask_b32_e64 v27, v149, v148, vcc
	v_mov_b32_dpp v222, v24 quad_perm:[1,0,3,2] row_mask:0xf bank_mask:0xf
	v_mov_b32_dpp v223, v25 quad_perm:[1,0,3,2] row_mask:0xf bank_mask:0xf
	v_mov_b32_dpp v224, v26 quad_perm:[1,0,3,2] row_mask:0xf bank_mask:0xf
	v_mov_b32_dpp v225, v27 quad_perm:[1,0,3,2] row_mask:0xf bank_mask:0xf
	v_cndmask_b32_e64 v142, v142, v222, vcc
	v_cndmask_b32_e64 v143, v222, v143, vcc
	v_cndmask_b32_e64 v144, v144, v223, vcc
	v_cndmask_b32_e64 v145, v223, v145, vcc
	v_cndmask_b32_e64 v146, v146, v224, vcc
	v_cndmask_b32_e64 v147, v224, v147, vcc
	v_cndmask_b32_e64 v148, v148, v225, vcc
	v_cndmask_b32_e64 v149, v225, v149, vcc
	v_cvt_pk_bf16_f32 v14, v142, v143
	v_cvt_pk_bf16_f32 v15, v144, v145
	v_cvt_pk_bf16_f32 v16, v146, v147
	v_cvt_pk_bf16_f32 v17, v148, v149
	v_lshlrev_b32_e32 v22, 16, v14
	v_and_b32_e32 v23, 0xffff0000, v14
	v_sub_f32_e32 v142, v142, v22
	v_sub_f32_e32 v143, v143, v23
	v_cvt_pk_bf16_f32 v18, v142, v143
	v_lshlrev_b32_e32 v22, 16, v15
	v_and_b32_e32 v23, 0xffff0000, v15
	v_sub_f32_e32 v144, v144, v22
	v_sub_f32_e32 v145, v145, v23
	v_cvt_pk_bf16_f32 v19, v144, v145
	v_lshlrev_b32_e32 v22, 16, v16
	v_and_b32_e32 v23, 0xffff0000, v16
	v_sub_f32_e32 v146, v146, v22
	v_sub_f32_e32 v147, v147, v23
	v_cvt_pk_bf16_f32 v20, v146, v147
	v_lshlrev_b32_e32 v22, 16, v17
	v_and_b32_e32 v23, 0xffff0000, v17
	v_sub_f32_e32 v148, v148, v22
	v_sub_f32_e32 v149, v149, v23
	v_cvt_pk_bf16_f32 v21, v148, v149
	global_load_dwordx2 v[142:143], v65, s[100:101] nt
	s_add_u32 s100, s100, 0xc000
	s_addc_u32 s101, s101, 0
	global_load_dwordx2 v[144:145], v65, s[100:101] nt
	s_add_u32 s100, s100, 0xc000
	s_addc_u32 s101, s101, 0
	global_load_dwordx2 v[146:147], v65, s[100:101] nt
	s_add_u32 s100, s100, 0xc000
	s_addc_u32 s101, s101, 0
	global_load_dwordx2 v[148:149], v65, s[100:101] nt
	s_add_u32 s100, s100, 0x9c000
	s_addc_u32 s101, s101, 0
	s_waitcnt lgkmcnt(0)
	v_mfma_f32_16x16x32_bf16 v[10:13], v[198:201], v[14:17], v[10:13]
	v_mfma_f32_16x16x32_bf16 v[6:9], v[206:209], v[14:17], v[6:9]
	v_mfma_f32_16x16x32_bf16 v[2:5], v[214:217], v[14:17], v[2:5]
	v_mfma_f32_16x16x32_bf16 v[10:13], v[198:201], v[18:21], v[10:13]
	ds_read_b128 v[198:201], v122 offset:640
	v_mfma_f32_16x16x32_bf16 v[6:9], v[206:209], v[18:21], v[6:9]
	ds_read_b128 v[206:209], v122 offset:33664
	v_mfma_f32_16x16x32_bf16 v[2:5], v[214:217], v[18:21], v[2:5]
	ds_read_b128 v[214:217], v28 offset:640
	v_mfma_f32_16x16x32_bf16 v[10:13], v[202:205], v[14:17], v[10:13]
	ds_read_b128 v[202:205], v123 offset:640
	v_mfma_f32_16x16x32_bf16 v[6:9], v[210:213], v[14:17], v[6:9]
	ds_read_b128 v[210:213], v123 offset:33664
	v_mfma_f32_16x16x32_bf16 v[2:5], v[218:221], v[14:17], v[2:5]
	ds_read_b128 v[218:221], v29 offset:640
	s_waitcnt vmcnt(60)
	v_cndmask_b32_e64 v24, v151, v150, vcc
	v_cndmask_b32_e64 v25, v153, v152, vcc
	v_cndmask_b32_e64 v26, v155, v154, vcc
	v_cndmask_b32_e64 v27, v157, v156, vcc
	v_mov_b32_dpp v222, v24 quad_perm:[1,0,3,2] row_mask:0xf bank_mask:0xf
	v_mov_b32_dpp v223, v25 quad_perm:[1,0,3,2] row_mask:0xf bank_mask:0xf
	v_mov_b32_dpp v224, v26 quad_perm:[1,0,3,2] row_mask:0xf bank_mask:0xf
	v_mov_b32_dpp v225, v27 quad_perm:[1,0,3,2] row_mask:0xf bank_mask:0xf
	v_cndmask_b32_e64 v150, v150, v222, vcc
	v_cndmask_b32_e64 v151, v222, v151, vcc
	v_cndmask_b32_e64 v152, v152, v223, vcc
	v_cndmask_b32_e64 v153, v223, v153, vcc
	v_cndmask_b32_e64 v154, v154, v224, vcc
	v_cndmask_b32_e64 v155, v224, v155, vcc
	v_cndmask_b32_e64 v156, v156, v225, vcc
	v_cndmask_b32_e64 v157, v225, v157, vcc
	v_cvt_pk_bf16_f32 v14, v150, v151
	v_cvt_pk_bf16_f32 v15, v152, v153
	v_cvt_pk_bf16_f32 v16, v154, v155
	v_cvt_pk_bf16_f32 v17, v156, v157
	v_lshlrev_b32_e32 v22, 16, v14
	v_and_b32_e32 v23, 0xffff0000, v14
	v_sub_f32_e32 v150, v150, v22
	v_sub_f32_e32 v151, v151, v23
	v_cvt_pk_bf16_f32 v18, v150, v151
	v_lshlrev_b32_e32 v22, 16, v15
	v_and_b32_e32 v23, 0xffff0000, v15
	v_sub_f32_e32 v152, v152, v22
	v_sub_f32_e32 v153, v153, v23
	v_cvt_pk_bf16_f32 v19, v152, v153
	v_lshlrev_b32_e32 v22, 16, v16
	v_and_b32_e32 v23, 0xffff0000, v16
	v_sub_f32_e32 v154, v154, v22
	v_sub_f32_e32 v155, v155, v23
	v_cvt_pk_bf16_f32 v20, v154, v155
	v_lshlrev_b32_e32 v22, 16, v17
	v_and_b32_e32 v23, 0xffff0000, v17
	v_sub_f32_e32 v156, v156, v22
	v_sub_f32_e32 v157, v157, v23
	v_cvt_pk_bf16_f32 v21, v156, v157
	global_load_dwordx2 v[150:151], v65, s[100:101] nt
	s_add_u32 s100, s100, 0xc000
	s_addc_u32 s101, s101, 0
	global_load_dwordx2 v[152:153], v65, s[100:101] nt
	s_add_u32 s100, s100, 0xc000
	s_addc_u32 s101, s101, 0
	global_load_dwordx2 v[154:155], v65, s[100:101] nt
	s_add_u32 s100, s100, 0xc000
	s_addc_u32 s101, s101, 0
	global_load_dwordx2 v[156:157], v65, s[100:101] nt
	s_add_u32 s100, s100, 0x9c000
	s_addc_u32 s101, s101, 0
	s_waitcnt lgkmcnt(0)
	v_mfma_f32_16x16x32_bf16 v[10:13], v[198:201], v[14:17], v[10:13]
	v_mfma_f32_16x16x32_bf16 v[6:9], v[206:209], v[14:17], v[6:9]
	v_mfma_f32_16x16x32_bf16 v[2:5], v[214:217], v[14:17], v[2:5]
	v_mfma_f32_16x16x32_bf16 v[10:13], v[198:201], v[18:21], v[10:13]
	ds_read_b128 v[198:201], v122 offset:704
	v_mfma_f32_16x16x32_bf16 v[6:9], v[206:209], v[18:21], v[6:9]
	ds_read_b128 v[206:209], v122 offset:33728
	v_mfma_f32_16x16x32_bf16 v[2:5], v[214:217], v[18:21], v[2:5]
	ds_read_b128 v[214:217], v28 offset:704
	v_mfma_f32_16x16x32_bf16 v[10:13], v[202:205], v[14:17], v[10:13]
	ds_read_b128 v[202:205], v123 offset:704
	v_mfma_f32_16x16x32_bf16 v[6:9], v[210:213], v[14:17], v[6:9]
	ds_read_b128 v[210:213], v123 offset:33728
	v_mfma_f32_16x16x32_bf16 v[2:5], v[218:221], v[14:17], v[2:5]
	ds_read_b128 v[218:221], v29 offset:704
	s_waitcnt vmcnt(60)
	v_cndmask_b32_e64 v24, v159, v158, vcc
	v_cndmask_b32_e64 v25, v161, v160, vcc
	v_cndmask_b32_e64 v26, v163, v162, vcc
	v_cndmask_b32_e64 v27, v165, v164, vcc
	v_mov_b32_dpp v222, v24 quad_perm:[1,0,3,2] row_mask:0xf bank_mask:0xf
	v_mov_b32_dpp v223, v25 quad_perm:[1,0,3,2] row_mask:0xf bank_mask:0xf
	v_mov_b32_dpp v224, v26 quad_perm:[1,0,3,2] row_mask:0xf bank_mask:0xf
	v_mov_b32_dpp v225, v27 quad_perm:[1,0,3,2] row_mask:0xf bank_mask:0xf
	v_cndmask_b32_e64 v158, v158, v222, vcc
	v_cndmask_b32_e64 v159, v222, v159, vcc
	v_cndmask_b32_e64 v160, v160, v223, vcc
	v_cndmask_b32_e64 v161, v223, v161, vcc
	v_cndmask_b32_e64 v162, v162, v224, vcc
	v_cndmask_b32_e64 v163, v224, v163, vcc
	v_cndmask_b32_e64 v164, v164, v225, vcc
	v_cndmask_b32_e64 v165, v225, v165, vcc
	v_cvt_pk_bf16_f32 v14, v158, v159
	v_cvt_pk_bf16_f32 v15, v160, v161
	v_cvt_pk_bf16_f32 v16, v162, v163
	v_cvt_pk_bf16_f32 v17, v164, v165
	v_lshlrev_b32_e32 v22, 16, v14
	v_and_b32_e32 v23, 0xffff0000, v14
	v_sub_f32_e32 v158, v158, v22
	v_sub_f32_e32 v159, v159, v23
	v_cvt_pk_bf16_f32 v18, v158, v159
	v_lshlrev_b32_e32 v22, 16, v15
	v_and_b32_e32 v23, 0xffff0000, v15
	v_sub_f32_e32 v160, v160, v22
	v_sub_f32_e32 v161, v161, v23
	v_cvt_pk_bf16_f32 v19, v160, v161
	v_lshlrev_b32_e32 v22, 16, v16
	v_and_b32_e32 v23, 0xffff0000, v16
	v_sub_f32_e32 v162, v162, v22
	v_sub_f32_e32 v163, v163, v23
	v_cvt_pk_bf16_f32 v20, v162, v163
	v_lshlrev_b32_e32 v22, 16, v17
	v_and_b32_e32 v23, 0xffff0000, v17
	v_sub_f32_e32 v164, v164, v22
	v_sub_f32_e32 v165, v165, v23
	v_cvt_pk_bf16_f32 v21, v164, v165
	global_load_dwordx2 v[158:159], v65, s[100:101] nt
	s_add_u32 s100, s100, 0xc000
	s_addc_u32 s101, s101, 0
	global_load_dwordx2 v[160:161], v65, s[100:101] nt
	s_add_u32 s100, s100, 0xc000
	s_addc_u32 s101, s101, 0
	global_load_dwordx2 v[162:163], v65, s[100:101] nt
	s_add_u32 s100, s100, 0xc000
	s_addc_u32 s101, s101, 0
	global_load_dwordx2 v[164:165], v65, s[100:101] nt
	s_add_u32 s100, s100, 0x9c000
	s_addc_u32 s101, s101, 0
	s_waitcnt lgkmcnt(0)
	v_mfma_f32_16x16x32_bf16 v[10:13], v[198:201], v[14:17], v[10:13]
	v_mfma_f32_16x16x32_bf16 v[6:9], v[206:209], v[14:17], v[6:9]
	v_mfma_f32_16x16x32_bf16 v[2:5], v[214:217], v[14:17], v[2:5]
	v_mfma_f32_16x16x32_bf16 v[10:13], v[198:201], v[18:21], v[10:13]
	ds_read_b128 v[198:201], v122 offset:768
	v_mfma_f32_16x16x32_bf16 v[6:9], v[206:209], v[18:21], v[6:9]
	ds_read_b128 v[206:209], v122 offset:33792
	v_mfma_f32_16x16x32_bf16 v[2:5], v[214:217], v[18:21], v[2:5]
	ds_read_b128 v[214:217], v28 offset:768
	v_mfma_f32_16x16x32_bf16 v[10:13], v[202:205], v[14:17], v[10:13]
	ds_read_b128 v[202:205], v123 offset:768
	v_mfma_f32_16x16x32_bf16 v[6:9], v[210:213], v[14:17], v[6:9]
	ds_read_b128 v[210:213], v123 offset:33792
	v_mfma_f32_16x16x32_bf16 v[2:5], v[218:221], v[14:17], v[2:5]
	ds_read_b128 v[218:221], v29 offset:768
	s_waitcnt vmcnt(60)
	v_cndmask_b32_e64 v24, v167, v166, vcc
	v_cndmask_b32_e64 v25, v169, v168, vcc
	v_cndmask_b32_e64 v26, v171, v170, vcc
	v_cndmask_b32_e64 v27, v173, v172, vcc
	v_mov_b32_dpp v222, v24 quad_perm:[1,0,3,2] row_mask:0xf bank_mask:0xf
	v_mov_b32_dpp v223, v25 quad_perm:[1,0,3,2] row_mask:0xf bank_mask:0xf
	v_mov_b32_dpp v224, v26 quad_perm:[1,0,3,2] row_mask:0xf bank_mask:0xf
	v_mov_b32_dpp v225, v27 quad_perm:[1,0,3,2] row_mask:0xf bank_mask:0xf
	v_cndmask_b32_e64 v166, v166, v222, vcc
	v_cndmask_b32_e64 v167, v222, v167, vcc
	v_cndmask_b32_e64 v168, v168, v223, vcc
	v_cndmask_b32_e64 v169, v223, v169, vcc
	v_cndmask_b32_e64 v170, v170, v224, vcc
	v_cndmask_b32_e64 v171, v224, v171, vcc
	v_cndmask_b32_e64 v172, v172, v225, vcc
	v_cndmask_b32_e64 v173, v225, v173, vcc
	v_cvt_pk_bf16_f32 v14, v166, v167
	v_cvt_pk_bf16_f32 v15, v168, v169
	v_cvt_pk_bf16_f32 v16, v170, v171
	v_cvt_pk_bf16_f32 v17, v172, v173
	v_lshlrev_b32_e32 v22, 16, v14
	v_and_b32_e32 v23, 0xffff0000, v14
	v_sub_f32_e32 v166, v166, v22
	v_sub_f32_e32 v167, v167, v23
	v_cvt_pk_bf16_f32 v18, v166, v167
	v_lshlrev_b32_e32 v22, 16, v15
	v_and_b32_e32 v23, 0xffff0000, v15
	v_sub_f32_e32 v168, v168, v22
	v_sub_f32_e32 v169, v169, v23
	v_cvt_pk_bf16_f32 v19, v168, v169
	v_lshlrev_b32_e32 v22, 16, v16
	v_and_b32_e32 v23, 0xffff0000, v16
	v_sub_f32_e32 v170, v170, v22
	v_sub_f32_e32 v171, v171, v23
	v_cvt_pk_bf16_f32 v20, v170, v171
	v_lshlrev_b32_e32 v22, 16, v17
	v_and_b32_e32 v23, 0xffff0000, v17
	v_sub_f32_e32 v172, v172, v22
	v_sub_f32_e32 v173, v173, v23
	v_cvt_pk_bf16_f32 v21, v172, v173
	global_load_dwordx2 v[166:167], v65, s[100:101] nt
	s_add_u32 s100, s100, 0xc000
	s_addc_u32 s101, s101, 0
	global_load_dwordx2 v[168:169], v65, s[100:101] nt
	s_add_u32 s100, s100, 0xc000
	s_addc_u32 s101, s101, 0
	global_load_dwordx2 v[170:171], v65, s[100:101] nt
	s_add_u32 s100, s100, 0xc000
	s_addc_u32 s101, s101, 0
	global_load_dwordx2 v[172:173], v65, s[100:101] nt
	s_add_u32 s100, s100, 0x9c000
	s_addc_u32 s101, s101, 0
	s_waitcnt lgkmcnt(0)
	v_mfma_f32_16x16x32_bf16 v[10:13], v[198:201], v[14:17], v[10:13]
	v_mfma_f32_16x16x32_bf16 v[6:9], v[206:209], v[14:17], v[6:9]
	v_mfma_f32_16x16x32_bf16 v[2:5], v[214:217], v[14:17], v[2:5]
	v_mfma_f32_16x16x32_bf16 v[10:13], v[198:201], v[18:21], v[10:13]
	ds_read_b128 v[198:201], v122 offset:832
	v_mfma_f32_16x16x32_bf16 v[6:9], v[206:209], v[18:21], v[6:9]
	ds_read_b128 v[206:209], v122 offset:33856
	v_mfma_f32_16x16x32_bf16 v[2:5], v[214:217], v[18:21], v[2:5]
	ds_read_b128 v[214:217], v28 offset:832
	v_mfma_f32_16x16x32_bf16 v[10:13], v[202:205], v[14:17], v[10:13]
	ds_read_b128 v[202:205], v123 offset:832
	v_mfma_f32_16x16x32_bf16 v[6:9], v[210:213], v[14:17], v[6:9]
	ds_read_b128 v[210:213], v123 offset:33856
	v_mfma_f32_16x16x32_bf16 v[2:5], v[218:221], v[14:17], v[2:5]
	ds_read_b128 v[218:221], v29 offset:832
	s_waitcnt vmcnt(60)
	v_cndmask_b32_e64 v24, v175, v174, vcc
	v_cndmask_b32_e64 v25, v177, v176, vcc
	v_cndmask_b32_e64 v26, v179, v178, vcc
	v_cndmask_b32_e64 v27, v181, v180, vcc
	v_mov_b32_dpp v222, v24 quad_perm:[1,0,3,2] row_mask:0xf bank_mask:0xf
	v_mov_b32_dpp v223, v25 quad_perm:[1,0,3,2] row_mask:0xf bank_mask:0xf
	v_mov_b32_dpp v224, v26 quad_perm:[1,0,3,2] row_mask:0xf bank_mask:0xf
	v_mov_b32_dpp v225, v27 quad_perm:[1,0,3,2] row_mask:0xf bank_mask:0xf
	v_cndmask_b32_e64 v174, v174, v222, vcc
	v_cndmask_b32_e64 v175, v222, v175, vcc
	v_cndmask_b32_e64 v176, v176, v223, vcc
	v_cndmask_b32_e64 v177, v223, v177, vcc
	v_cndmask_b32_e64 v178, v178, v224, vcc
	v_cndmask_b32_e64 v179, v224, v179, vcc
	v_cndmask_b32_e64 v180, v180, v225, vcc
	v_cndmask_b32_e64 v181, v225, v181, vcc
	v_cvt_pk_bf16_f32 v14, v174, v175
	v_cvt_pk_bf16_f32 v15, v176, v177
	v_cvt_pk_bf16_f32 v16, v178, v179
	v_cvt_pk_bf16_f32 v17, v180, v181
	v_lshlrev_b32_e32 v22, 16, v14
	v_and_b32_e32 v23, 0xffff0000, v14
	v_sub_f32_e32 v174, v174, v22
	v_sub_f32_e32 v175, v175, v23
	v_cvt_pk_bf16_f32 v18, v174, v175
	v_lshlrev_b32_e32 v22, 16, v15
	v_and_b32_e32 v23, 0xffff0000, v15
	v_sub_f32_e32 v176, v176, v22
	v_sub_f32_e32 v177, v177, v23
	v_cvt_pk_bf16_f32 v19, v176, v177
	v_lshlrev_b32_e32 v22, 16, v16
	v_and_b32_e32 v23, 0xffff0000, v16
	v_sub_f32_e32 v178, v178, v22
	v_sub_f32_e32 v179, v179, v23
	v_cvt_pk_bf16_f32 v20, v178, v179
	v_lshlrev_b32_e32 v22, 16, v17
	v_and_b32_e32 v23, 0xffff0000, v17
	v_sub_f32_e32 v180, v180, v22
	v_sub_f32_e32 v181, v181, v23
	v_cvt_pk_bf16_f32 v21, v180, v181
	global_load_dwordx2 v[174:175], v65, s[100:101] nt
	s_add_u32 s100, s100, 0xc000
	s_addc_u32 s101, s101, 0
	global_load_dwordx2 v[176:177], v65, s[100:101] nt
	s_add_u32 s100, s100, 0xc000
	s_addc_u32 s101, s101, 0
	global_load_dwordx2 v[178:179], v65, s[100:101] nt
	s_add_u32 s100, s100, 0xc000
	s_addc_u32 s101, s101, 0
	global_load_dwordx2 v[180:181], v65, s[100:101] nt
	s_add_u32 s100, s100, 0x9c000
	s_addc_u32 s101, s101, 0
	s_waitcnt lgkmcnt(0)
	v_mfma_f32_16x16x32_bf16 v[10:13], v[198:201], v[14:17], v[10:13]
	v_mfma_f32_16x16x32_bf16 v[6:9], v[206:209], v[14:17], v[6:9]
	v_mfma_f32_16x16x32_bf16 v[2:5], v[214:217], v[14:17], v[2:5]
	v_mfma_f32_16x16x32_bf16 v[10:13], v[198:201], v[18:21], v[10:13]
	ds_read_b128 v[198:201], v122 offset:896
	v_mfma_f32_16x16x32_bf16 v[6:9], v[206:209], v[18:21], v[6:9]
	ds_read_b128 v[206:209], v122 offset:33920
	v_mfma_f32_16x16x32_bf16 v[2:5], v[214:217], v[18:21], v[2:5]
	ds_read_b128 v[214:217], v28 offset:896
	v_mfma_f32_16x16x32_bf16 v[10:13], v[202:205], v[14:17], v[10:13]
	ds_read_b128 v[202:205], v123 offset:896
	v_mfma_f32_16x16x32_bf16 v[6:9], v[210:213], v[14:17], v[6:9]
	ds_read_b128 v[210:213], v123 offset:33920
	v_mfma_f32_16x16x32_bf16 v[2:5], v[218:221], v[14:17], v[2:5]
	ds_read_b128 v[218:221], v29 offset:896
	s_waitcnt vmcnt(60)
	v_cndmask_b32_e64 v24, v183, v182, vcc
	v_cndmask_b32_e64 v25, v185, v184, vcc
	v_cndmask_b32_e64 v26, v187, v186, vcc
	v_cndmask_b32_e64 v27, v189, v188, vcc
	v_mov_b32_dpp v222, v24 quad_perm:[1,0,3,2] row_mask:0xf bank_mask:0xf
	v_mov_b32_dpp v223, v25 quad_perm:[1,0,3,2] row_mask:0xf bank_mask:0xf
	v_mov_b32_dpp v224, v26 quad_perm:[1,0,3,2] row_mask:0xf bank_mask:0xf
	v_mov_b32_dpp v225, v27 quad_perm:[1,0,3,2] row_mask:0xf bank_mask:0xf
	v_cndmask_b32_e64 v182, v182, v222, vcc
	v_cndmask_b32_e64 v183, v222, v183, vcc
	v_cndmask_b32_e64 v184, v184, v223, vcc
	v_cndmask_b32_e64 v185, v223, v185, vcc
	v_cndmask_b32_e64 v186, v186, v224, vcc
	v_cndmask_b32_e64 v187, v224, v187, vcc
	v_cndmask_b32_e64 v188, v188, v225, vcc
	v_cndmask_b32_e64 v189, v225, v189, vcc
	v_cvt_pk_bf16_f32 v14, v182, v183
	v_cvt_pk_bf16_f32 v15, v184, v185
	v_cvt_pk_bf16_f32 v16, v186, v187
	v_cvt_pk_bf16_f32 v17, v188, v189
	v_lshlrev_b32_e32 v22, 16, v14
	v_and_b32_e32 v23, 0xffff0000, v14
	v_sub_f32_e32 v182, v182, v22
	v_sub_f32_e32 v183, v183, v23
	v_cvt_pk_bf16_f32 v18, v182, v183
	v_lshlrev_b32_e32 v22, 16, v15
	v_and_b32_e32 v23, 0xffff0000, v15
	v_sub_f32_e32 v184, v184, v22
	v_sub_f32_e32 v185, v185, v23
	v_cvt_pk_bf16_f32 v19, v184, v185
	v_lshlrev_b32_e32 v22, 16, v16
	v_and_b32_e32 v23, 0xffff0000, v16
	v_sub_f32_e32 v186, v186, v22
	v_sub_f32_e32 v187, v187, v23
	v_cvt_pk_bf16_f32 v20, v186, v187
	v_lshlrev_b32_e32 v22, 16, v17
	v_and_b32_e32 v23, 0xffff0000, v17
	v_sub_f32_e32 v188, v188, v22
	v_sub_f32_e32 v189, v189, v23
	v_cvt_pk_bf16_f32 v21, v188, v189
	global_load_dwordx2 v[182:183], v65, s[100:101] nt
	s_add_u32 s100, s100, 0xc000
	s_addc_u32 s101, s101, 0
	global_load_dwordx2 v[184:185], v65, s[100:101] nt
	s_add_u32 s100, s100, 0xc000
	s_addc_u32 s101, s101, 0
	global_load_dwordx2 v[186:187], v65, s[100:101] nt
	s_add_u32 s100, s100, 0xc000
	s_addc_u32 s101, s101, 0
	global_load_dwordx2 v[188:189], v65, s[100:101] nt
	s_add_u32 s100, s100, 0x9c000
	s_addc_u32 s101, s101, 0
	s_waitcnt lgkmcnt(0)
	v_mfma_f32_16x16x32_bf16 v[10:13], v[198:201], v[14:17], v[10:13]
	v_mfma_f32_16x16x32_bf16 v[6:9], v[206:209], v[14:17], v[6:9]
	v_mfma_f32_16x16x32_bf16 v[2:5], v[214:217], v[14:17], v[2:5]
	v_mfma_f32_16x16x32_bf16 v[10:13], v[198:201], v[18:21], v[10:13]
	ds_read_b128 v[198:201], v122 offset:960
	v_mfma_f32_16x16x32_bf16 v[6:9], v[206:209], v[18:21], v[6:9]
	ds_read_b128 v[206:209], v122 offset:33984
	v_mfma_f32_16x16x32_bf16 v[2:5], v[214:217], v[18:21], v[2:5]
	ds_read_b128 v[214:217], v28 offset:960
	v_mfma_f32_16x16x32_bf16 v[10:13], v[202:205], v[14:17], v[10:13]
	ds_read_b128 v[202:205], v123 offset:960
	v_mfma_f32_16x16x32_bf16 v[6:9], v[210:213], v[14:17], v[6:9]
	ds_read_b128 v[210:213], v123 offset:33984
	v_mfma_f32_16x16x32_bf16 v[2:5], v[218:221], v[14:17], v[2:5]
	ds_read_b128 v[218:221], v29 offset:960
	s_waitcnt vmcnt(60)
	v_cndmask_b32_e64 v24, v191, v190, vcc
	v_cndmask_b32_e64 v25, v193, v192, vcc
	v_cndmask_b32_e64 v26, v195, v194, vcc
	v_cndmask_b32_e64 v27, v197, v196, vcc
	v_mov_b32_dpp v222, v24 quad_perm:[1,0,3,2] row_mask:0xf bank_mask:0xf
	v_mov_b32_dpp v223, v25 quad_perm:[1,0,3,2] row_mask:0xf bank_mask:0xf
	v_mov_b32_dpp v224, v26 quad_perm:[1,0,3,2] row_mask:0xf bank_mask:0xf
	v_mov_b32_dpp v225, v27 quad_perm:[1,0,3,2] row_mask:0xf bank_mask:0xf
	v_cndmask_b32_e64 v190, v190, v222, vcc
	v_cndmask_b32_e64 v191, v222, v191, vcc
	v_cndmask_b32_e64 v192, v192, v223, vcc
	v_cndmask_b32_e64 v193, v223, v193, vcc
	v_cndmask_b32_e64 v194, v194, v224, vcc
	v_cndmask_b32_e64 v195, v224, v195, vcc
	v_cndmask_b32_e64 v196, v196, v225, vcc
	v_cndmask_b32_e64 v197, v225, v197, vcc
	v_cvt_pk_bf16_f32 v14, v190, v191
	v_cvt_pk_bf16_f32 v15, v192, v193
	v_cvt_pk_bf16_f32 v16, v194, v195
	v_cvt_pk_bf16_f32 v17, v196, v197
	v_lshlrev_b32_e32 v22, 16, v14
	v_and_b32_e32 v23, 0xffff0000, v14
	v_sub_f32_e32 v190, v190, v22
	v_sub_f32_e32 v191, v191, v23
	v_cvt_pk_bf16_f32 v18, v190, v191
	v_lshlrev_b32_e32 v22, 16, v15
	v_and_b32_e32 v23, 0xffff0000, v15
	v_sub_f32_e32 v192, v192, v22
	v_sub_f32_e32 v193, v193, v23
	v_cvt_pk_bf16_f32 v19, v192, v193
	v_lshlrev_b32_e32 v22, 16, v16
	v_and_b32_e32 v23, 0xffff0000, v16
	v_sub_f32_e32 v194, v194, v22
	v_sub_f32_e32 v195, v195, v23
	v_cvt_pk_bf16_f32 v20, v194, v195
	v_lshlrev_b32_e32 v22, 16, v17
	v_and_b32_e32 v23, 0xffff0000, v17
	v_sub_f32_e32 v196, v196, v22
	v_sub_f32_e32 v197, v197, v23
	v_cvt_pk_bf16_f32 v21, v196, v197
	global_load_dwordx2 v[190:191], v65, s[100:101] nt
	s_add_u32 s100, s100, 0xc000
	s_addc_u32 s101, s101, 0
	global_load_dwordx2 v[192:193], v65, s[100:101] nt
	s_add_u32 s100, s100, 0xc000
	s_addc_u32 s101, s101, 0
	global_load_dwordx2 v[194:195], v65, s[100:101] nt
	s_add_u32 s100, s100, 0xc000
	s_addc_u32 s101, s101, 0
	global_load_dwordx2 v[196:197], v65, s[100:101] nt
	s_add_u32 s100, s100, 0x9c000
	s_addc_u32 s101, s101, 0
	s_waitcnt lgkmcnt(0)
	v_mfma_f32_16x16x32_bf16 v[10:13], v[198:201], v[14:17], v[10:13]
	v_mfma_f32_16x16x32_bf16 v[6:9], v[206:209], v[14:17], v[6:9]
	v_mfma_f32_16x16x32_bf16 v[2:5], v[214:217], v[14:17], v[2:5]
	v_mfma_f32_16x16x32_bf16 v[10:13], v[198:201], v[18:21], v[10:13]
	ds_read_b128 v[198:201], v122 offset:1024
	v_mfma_f32_16x16x32_bf16 v[6:9], v[206:209], v[18:21], v[6:9]
	ds_read_b128 v[206:209], v122 offset:34048
	v_mfma_f32_16x16x32_bf16 v[2:5], v[214:217], v[18:21], v[2:5]
	ds_read_b128 v[214:217], v28 offset:1024
	v_mfma_f32_16x16x32_bf16 v[10:13], v[202:205], v[14:17], v[10:13]
	ds_read_b128 v[202:205], v123 offset:1024
	v_mfma_f32_16x16x32_bf16 v[6:9], v[210:213], v[14:17], v[6:9]
	ds_read_b128 v[210:213], v123 offset:34048
	v_mfma_f32_16x16x32_bf16 v[2:5], v[218:221], v[14:17], v[2:5]
	ds_read_b128 v[218:221], v29 offset:1024
	s_waitcnt vmcnt(60)
	v_cndmask_b32_e64 v24, v67, v66, vcc
	v_cndmask_b32_e64 v25, v69, v68, vcc
	v_cndmask_b32_e64 v26, v71, v70, vcc
	v_cndmask_b32_e64 v27, v73, v72, vcc
	v_mov_b32_dpp v222, v24 quad_perm:[1,0,3,2] row_mask:0xf bank_mask:0xf
	v_mov_b32_dpp v223, v25 quad_perm:[1,0,3,2] row_mask:0xf bank_mask:0xf
	v_mov_b32_dpp v224, v26 quad_perm:[1,0,3,2] row_mask:0xf bank_mask:0xf
	v_mov_b32_dpp v225, v27 quad_perm:[1,0,3,2] row_mask:0xf bank_mask:0xf
	v_cndmask_b32_e64 v66, v66, v222, vcc
	v_cndmask_b32_e64 v67, v222, v67, vcc
	v_cndmask_b32_e64 v68, v68, v223, vcc
	v_cndmask_b32_e64 v69, v223, v69, vcc
	v_cndmask_b32_e64 v70, v70, v224, vcc
	v_cndmask_b32_e64 v71, v224, v71, vcc
	v_cndmask_b32_e64 v72, v72, v225, vcc
	v_cndmask_b32_e64 v73, v225, v73, vcc
	v_cvt_pk_bf16_f32 v14, v66, v67
	v_cvt_pk_bf16_f32 v15, v68, v69
	v_cvt_pk_bf16_f32 v16, v70, v71
	v_cvt_pk_bf16_f32 v17, v72, v73
	v_lshlrev_b32_e32 v22, 16, v14
	v_and_b32_e32 v23, 0xffff0000, v14
	v_sub_f32_e32 v66, v66, v22
	v_sub_f32_e32 v67, v67, v23
	v_cvt_pk_bf16_f32 v18, v66, v67
	v_lshlrev_b32_e32 v22, 16, v15
	v_and_b32_e32 v23, 0xffff0000, v15
	v_sub_f32_e32 v68, v68, v22
	v_sub_f32_e32 v69, v69, v23
	v_cvt_pk_bf16_f32 v19, v68, v69
	v_lshlrev_b32_e32 v22, 16, v16
	v_and_b32_e32 v23, 0xffff0000, v16
	v_sub_f32_e32 v70, v70, v22
	v_sub_f32_e32 v71, v71, v23
	v_cvt_pk_bf16_f32 v20, v70, v71
	v_lshlrev_b32_e32 v22, 16, v17
	v_and_b32_e32 v23, 0xffff0000, v17
	v_sub_f32_e32 v72, v72, v22
	v_sub_f32_e32 v73, v73, v23
	v_cvt_pk_bf16_f32 v21, v72, v73
	s_waitcnt lgkmcnt(0)
	v_mfma_f32_16x16x32_bf16 v[10:13], v[198:201], v[14:17], v[10:13]
	v_mfma_f32_16x16x32_bf16 v[6:9], v[206:209], v[14:17], v[6:9]
	v_mfma_f32_16x16x32_bf16 v[2:5], v[214:217], v[14:17], v[2:5]
	v_mfma_f32_16x16x32_bf16 v[10:13], v[198:201], v[18:21], v[10:13]
	ds_read_b128 v[198:201], v122 offset:1088
	v_mfma_f32_16x16x32_bf16 v[6:9], v[206:209], v[18:21], v[6:9]
	ds_read_b128 v[206:209], v122 offset:34112
	v_mfma_f32_16x16x32_bf16 v[2:5], v[214:217], v[18:21], v[2:5]
	ds_read_b128 v[214:217], v28 offset:1088
	v_mfma_f32_16x16x32_bf16 v[10:13], v[202:205], v[14:17], v[10:13]
	ds_read_b128 v[202:205], v123 offset:1088
	v_mfma_f32_16x16x32_bf16 v[6:9], v[210:213], v[14:17], v[6:9]
	ds_read_b128 v[210:213], v123 offset:34112
	v_mfma_f32_16x16x32_bf16 v[2:5], v[218:221], v[14:17], v[2:5]
	ds_read_b128 v[218:221], v29 offset:1088
	s_waitcnt vmcnt(56)
	v_cndmask_b32_e64 v24, v75, v74, vcc
	v_cndmask_b32_e64 v25, v77, v76, vcc
	v_cndmask_b32_e64 v26, v79, v78, vcc
	v_cndmask_b32_e64 v27, v81, v80, vcc
	v_mov_b32_dpp v222, v24 quad_perm:[1,0,3,2] row_mask:0xf bank_mask:0xf
	v_mov_b32_dpp v223, v25 quad_perm:[1,0,3,2] row_mask:0xf bank_mask:0xf
	v_mov_b32_dpp v224, v26 quad_perm:[1,0,3,2] row_mask:0xf bank_mask:0xf
	v_mov_b32_dpp v225, v27 quad_perm:[1,0,3,2] row_mask:0xf bank_mask:0xf
	v_cndmask_b32_e64 v74, v74, v222, vcc
	v_cndmask_b32_e64 v75, v222, v75, vcc
	v_cndmask_b32_e64 v76, v76, v223, vcc
	v_cndmask_b32_e64 v77, v223, v77, vcc
	v_cndmask_b32_e64 v78, v78, v224, vcc
	v_cndmask_b32_e64 v79, v224, v79, vcc
	v_cndmask_b32_e64 v80, v80, v225, vcc
	v_cndmask_b32_e64 v81, v225, v81, vcc
	v_cvt_pk_bf16_f32 v14, v74, v75
	v_cvt_pk_bf16_f32 v15, v76, v77
	v_cvt_pk_bf16_f32 v16, v78, v79
	v_cvt_pk_bf16_f32 v17, v80, v81
	v_lshlrev_b32_e32 v22, 16, v14
	v_and_b32_e32 v23, 0xffff0000, v14
	v_sub_f32_e32 v74, v74, v22
	v_sub_f32_e32 v75, v75, v23
	v_cvt_pk_bf16_f32 v18, v74, v75
	v_lshlrev_b32_e32 v22, 16, v15
	v_and_b32_e32 v23, 0xffff0000, v15
	v_sub_f32_e32 v76, v76, v22
	v_sub_f32_e32 v77, v77, v23
	v_cvt_pk_bf16_f32 v19, v76, v77
	v_lshlrev_b32_e32 v22, 16, v16
	v_and_b32_e32 v23, 0xffff0000, v16
	v_sub_f32_e32 v78, v78, v22
	v_sub_f32_e32 v79, v79, v23
	v_cvt_pk_bf16_f32 v20, v78, v79
	v_lshlrev_b32_e32 v22, 16, v17
	v_and_b32_e32 v23, 0xffff0000, v17
	v_sub_f32_e32 v80, v80, v22
	v_sub_f32_e32 v81, v81, v23
	v_cvt_pk_bf16_f32 v21, v80, v81
	s_waitcnt lgkmcnt(0)
	v_mfma_f32_16x16x32_bf16 v[10:13], v[198:201], v[14:17], v[10:13]
	v_mfma_f32_16x16x32_bf16 v[6:9], v[206:209], v[14:17], v[6:9]
	v_mfma_f32_16x16x32_bf16 v[2:5], v[214:217], v[14:17], v[2:5]
	v_mfma_f32_16x16x32_bf16 v[10:13], v[198:201], v[18:21], v[10:13]
	ds_read_b128 v[198:201], v122 offset:1152
	v_mfma_f32_16x16x32_bf16 v[6:9], v[206:209], v[18:21], v[6:9]
	ds_read_b128 v[206:209], v122 offset:34176
	v_mfma_f32_16x16x32_bf16 v[2:5], v[214:217], v[18:21], v[2:5]
	ds_read_b128 v[214:217], v28 offset:1152
	v_mfma_f32_16x16x32_bf16 v[10:13], v[202:205], v[14:17], v[10:13]
	ds_read_b128 v[202:205], v123 offset:1152
	v_mfma_f32_16x16x32_bf16 v[6:9], v[210:213], v[14:17], v[6:9]
	ds_read_b128 v[210:213], v123 offset:34176
	v_mfma_f32_16x16x32_bf16 v[2:5], v[218:221], v[14:17], v[2:5]
	ds_read_b128 v[218:221], v29 offset:1152
	s_waitcnt vmcnt(52)
	v_cndmask_b32_e64 v24, v83, v82, vcc
	v_cndmask_b32_e64 v25, v85, v84, vcc
	v_cndmask_b32_e64 v26, v87, v86, vcc
	v_cndmask_b32_e64 v27, v89, v88, vcc
	v_mov_b32_dpp v222, v24 quad_perm:[1,0,3,2] row_mask:0xf bank_mask:0xf
	v_mov_b32_dpp v223, v25 quad_perm:[1,0,3,2] row_mask:0xf bank_mask:0xf
	v_mov_b32_dpp v224, v26 quad_perm:[1,0,3,2] row_mask:0xf bank_mask:0xf
	v_mov_b32_dpp v225, v27 quad_perm:[1,0,3,2] row_mask:0xf bank_mask:0xf
	v_cndmask_b32_e64 v82, v82, v222, vcc
	v_cndmask_b32_e64 v83, v222, v83, vcc
	v_cndmask_b32_e64 v84, v84, v223, vcc
	v_cndmask_b32_e64 v85, v223, v85, vcc
	v_cndmask_b32_e64 v86, v86, v224, vcc
	v_cndmask_b32_e64 v87, v224, v87, vcc
	v_cndmask_b32_e64 v88, v88, v225, vcc
	v_cndmask_b32_e64 v89, v225, v89, vcc
	v_cvt_pk_bf16_f32 v14, v82, v83
	v_cvt_pk_bf16_f32 v15, v84, v85
	v_cvt_pk_bf16_f32 v16, v86, v87
	v_cvt_pk_bf16_f32 v17, v88, v89
	v_lshlrev_b32_e32 v22, 16, v14
	v_and_b32_e32 v23, 0xffff0000, v14
	v_sub_f32_e32 v82, v82, v22
	v_sub_f32_e32 v83, v83, v23
	v_cvt_pk_bf16_f32 v18, v82, v83
	v_lshlrev_b32_e32 v22, 16, v15
	v_and_b32_e32 v23, 0xffff0000, v15
	v_sub_f32_e32 v84, v84, v22
	v_sub_f32_e32 v85, v85, v23
	v_cvt_pk_bf16_f32 v19, v84, v85
	v_lshlrev_b32_e32 v22, 16, v16
	v_and_b32_e32 v23, 0xffff0000, v16
	v_sub_f32_e32 v86, v86, v22
	v_sub_f32_e32 v87, v87, v23
	v_cvt_pk_bf16_f32 v20, v86, v87
	v_lshlrev_b32_e32 v22, 16, v17
	v_and_b32_e32 v23, 0xffff0000, v17
	v_sub_f32_e32 v88, v88, v22
	v_sub_f32_e32 v89, v89, v23
	v_cvt_pk_bf16_f32 v21, v88, v89
	s_waitcnt lgkmcnt(0)
	v_mfma_f32_16x16x32_bf16 v[10:13], v[198:201], v[14:17], v[10:13]
	v_mfma_f32_16x16x32_bf16 v[6:9], v[206:209], v[14:17], v[6:9]
	v_mfma_f32_16x16x32_bf16 v[2:5], v[214:217], v[14:17], v[2:5]
	v_mfma_f32_16x16x32_bf16 v[10:13], v[198:201], v[18:21], v[10:13]
	ds_read_b128 v[198:201], v122 offset:1216
	v_mfma_f32_16x16x32_bf16 v[6:9], v[206:209], v[18:21], v[6:9]
	ds_read_b128 v[206:209], v122 offset:34240
	v_mfma_f32_16x16x32_bf16 v[2:5], v[214:217], v[18:21], v[2:5]
	ds_read_b128 v[214:217], v28 offset:1216
	v_mfma_f32_16x16x32_bf16 v[10:13], v[202:205], v[14:17], v[10:13]
	ds_read_b128 v[202:205], v123 offset:1216
	v_mfma_f32_16x16x32_bf16 v[6:9], v[210:213], v[14:17], v[6:9]
	ds_read_b128 v[210:213], v123 offset:34240
	v_mfma_f32_16x16x32_bf16 v[2:5], v[218:221], v[14:17], v[2:5]
	ds_read_b128 v[218:221], v29 offset:1216
	s_waitcnt vmcnt(48)
	v_cndmask_b32_e64 v24, v91, v90, vcc
	v_cndmask_b32_e64 v25, v93, v92, vcc
	v_cndmask_b32_e64 v26, v95, v94, vcc
	v_cndmask_b32_e64 v27, v97, v96, vcc
	v_mov_b32_dpp v222, v24 quad_perm:[1,0,3,2] row_mask:0xf bank_mask:0xf
	v_mov_b32_dpp v223, v25 quad_perm:[1,0,3,2] row_mask:0xf bank_mask:0xf
	v_mov_b32_dpp v224, v26 quad_perm:[1,0,3,2] row_mask:0xf bank_mask:0xf
	v_mov_b32_dpp v225, v27 quad_perm:[1,0,3,2] row_mask:0xf bank_mask:0xf
	v_cndmask_b32_e64 v90, v90, v222, vcc
	v_cndmask_b32_e64 v91, v222, v91, vcc
	v_cndmask_b32_e64 v92, v92, v223, vcc
	v_cndmask_b32_e64 v93, v223, v93, vcc
	v_cndmask_b32_e64 v94, v94, v224, vcc
	v_cndmask_b32_e64 v95, v224, v95, vcc
	v_cndmask_b32_e64 v96, v96, v225, vcc
	v_cndmask_b32_e64 v97, v225, v97, vcc
	v_cvt_pk_bf16_f32 v14, v90, v91
	v_cvt_pk_bf16_f32 v15, v92, v93
	v_cvt_pk_bf16_f32 v16, v94, v95
	v_cvt_pk_bf16_f32 v17, v96, v97
	v_lshlrev_b32_e32 v22, 16, v14
	v_and_b32_e32 v23, 0xffff0000, v14
	v_sub_f32_e32 v90, v90, v22
	v_sub_f32_e32 v91, v91, v23
	v_cvt_pk_bf16_f32 v18, v90, v91
	v_lshlrev_b32_e32 v22, 16, v15
	v_and_b32_e32 v23, 0xffff0000, v15
	v_sub_f32_e32 v92, v92, v22
	v_sub_f32_e32 v93, v93, v23
	v_cvt_pk_bf16_f32 v19, v92, v93
	v_lshlrev_b32_e32 v22, 16, v16
	v_and_b32_e32 v23, 0xffff0000, v16
	v_sub_f32_e32 v94, v94, v22
	v_sub_f32_e32 v95, v95, v23
	v_cvt_pk_bf16_f32 v20, v94, v95
	v_lshlrev_b32_e32 v22, 16, v17
	v_and_b32_e32 v23, 0xffff0000, v17
	v_sub_f32_e32 v96, v96, v22
	v_sub_f32_e32 v97, v97, v23
	v_cvt_pk_bf16_f32 v21, v96, v97
	s_waitcnt lgkmcnt(0)
	v_mfma_f32_16x16x32_bf16 v[10:13], v[198:201], v[14:17], v[10:13]
	v_mfma_f32_16x16x32_bf16 v[6:9], v[206:209], v[14:17], v[6:9]
	v_mfma_f32_16x16x32_bf16 v[2:5], v[214:217], v[14:17], v[2:5]
	v_mfma_f32_16x16x32_bf16 v[10:13], v[198:201], v[18:21], v[10:13]
	ds_read_b128 v[198:201], v122 offset:1280
	v_mfma_f32_16x16x32_bf16 v[6:9], v[206:209], v[18:21], v[6:9]
	ds_read_b128 v[206:209], v122 offset:34304
	v_mfma_f32_16x16x32_bf16 v[2:5], v[214:217], v[18:21], v[2:5]
	ds_read_b128 v[214:217], v28 offset:1280
	v_mfma_f32_16x16x32_bf16 v[10:13], v[202:205], v[14:17], v[10:13]
	ds_read_b128 v[202:205], v123 offset:1280
	v_mfma_f32_16x16x32_bf16 v[6:9], v[210:213], v[14:17], v[6:9]
	ds_read_b128 v[210:213], v123 offset:34304
	v_mfma_f32_16x16x32_bf16 v[2:5], v[218:221], v[14:17], v[2:5]
	ds_read_b128 v[218:221], v29 offset:1280
	s_waitcnt vmcnt(44)
	v_cndmask_b32_e64 v24, v99, v98, vcc
	v_cndmask_b32_e64 v25, v101, v100, vcc
	v_cndmask_b32_e64 v26, v103, v102, vcc
	v_cndmask_b32_e64 v27, v105, v104, vcc
	v_mov_b32_dpp v222, v24 quad_perm:[1,0,3,2] row_mask:0xf bank_mask:0xf
	v_mov_b32_dpp v223, v25 quad_perm:[1,0,3,2] row_mask:0xf bank_mask:0xf
	v_mov_b32_dpp v224, v26 quad_perm:[1,0,3,2] row_mask:0xf bank_mask:0xf
	v_mov_b32_dpp v225, v27 quad_perm:[1,0,3,2] row_mask:0xf bank_mask:0xf
	v_cndmask_b32_e64 v98, v98, v222, vcc
	v_cndmask_b32_e64 v99, v222, v99, vcc
	v_cndmask_b32_e64 v100, v100, v223, vcc
	v_cndmask_b32_e64 v101, v223, v101, vcc
	v_cndmask_b32_e64 v102, v102, v224, vcc
	v_cndmask_b32_e64 v103, v224, v103, vcc
	v_cndmask_b32_e64 v104, v104, v225, vcc
	v_cndmask_b32_e64 v105, v225, v105, vcc
	v_cvt_pk_bf16_f32 v14, v98, v99
	v_cvt_pk_bf16_f32 v15, v100, v101
	v_cvt_pk_bf16_f32 v16, v102, v103
	v_cvt_pk_bf16_f32 v17, v104, v105
	v_lshlrev_b32_e32 v22, 16, v14
	v_and_b32_e32 v23, 0xffff0000, v14
	v_sub_f32_e32 v98, v98, v22
	v_sub_f32_e32 v99, v99, v23
	v_cvt_pk_bf16_f32 v18, v98, v99
	v_lshlrev_b32_e32 v22, 16, v15
	v_and_b32_e32 v23, 0xffff0000, v15
	v_sub_f32_e32 v100, v100, v22
	v_sub_f32_e32 v101, v101, v23
	v_cvt_pk_bf16_f32 v19, v100, v101
	v_lshlrev_b32_e32 v22, 16, v16
	v_and_b32_e32 v23, 0xffff0000, v16
	v_sub_f32_e32 v102, v102, v22
	v_sub_f32_e32 v103, v103, v23
	v_cvt_pk_bf16_f32 v20, v102, v103
	v_lshlrev_b32_e32 v22, 16, v17
	v_and_b32_e32 v23, 0xffff0000, v17
	v_sub_f32_e32 v104, v104, v22
	v_sub_f32_e32 v105, v105, v23
	v_cvt_pk_bf16_f32 v21, v104, v105
	s_waitcnt lgkmcnt(0)
	v_mfma_f32_16x16x32_bf16 v[10:13], v[198:201], v[14:17], v[10:13]
	v_mfma_f32_16x16x32_bf16 v[6:9], v[206:209], v[14:17], v[6:9]
	v_mfma_f32_16x16x32_bf16 v[2:5], v[214:217], v[14:17], v[2:5]
	v_mfma_f32_16x16x32_bf16 v[10:13], v[198:201], v[18:21], v[10:13]
	ds_read_b128 v[198:201], v122 offset:1344
	v_mfma_f32_16x16x32_bf16 v[6:9], v[206:209], v[18:21], v[6:9]
	ds_read_b128 v[206:209], v122 offset:34368
	v_mfma_f32_16x16x32_bf16 v[2:5], v[214:217], v[18:21], v[2:5]
	ds_read_b128 v[214:217], v28 offset:1344
	v_mfma_f32_16x16x32_bf16 v[10:13], v[202:205], v[14:17], v[10:13]
	ds_read_b128 v[202:205], v123 offset:1344
	v_mfma_f32_16x16x32_bf16 v[6:9], v[210:213], v[14:17], v[6:9]
	ds_read_b128 v[210:213], v123 offset:34368
	v_mfma_f32_16x16x32_bf16 v[2:5], v[218:221], v[14:17], v[2:5]
	ds_read_b128 v[218:221], v29 offset:1344
	s_waitcnt vmcnt(40)
	v_cndmask_b32_e64 v24, v107, v106, vcc
	v_cndmask_b32_e64 v25, v109, v108, vcc
	v_cndmask_b32_e64 v26, v111, v110, vcc
	v_cndmask_b32_e64 v27, v113, v112, vcc
	v_mov_b32_dpp v222, v24 quad_perm:[1,0,3,2] row_mask:0xf bank_mask:0xf
	v_mov_b32_dpp v223, v25 quad_perm:[1,0,3,2] row_mask:0xf bank_mask:0xf
	v_mov_b32_dpp v224, v26 quad_perm:[1,0,3,2] row_mask:0xf bank_mask:0xf
	v_mov_b32_dpp v225, v27 quad_perm:[1,0,3,2] row_mask:0xf bank_mask:0xf
	v_cndmask_b32_e64 v106, v106, v222, vcc
	v_cndmask_b32_e64 v107, v222, v107, vcc
	v_cndmask_b32_e64 v108, v108, v223, vcc
	v_cndmask_b32_e64 v109, v223, v109, vcc
	v_cndmask_b32_e64 v110, v110, v224, vcc
	v_cndmask_b32_e64 v111, v224, v111, vcc
	v_cndmask_b32_e64 v112, v112, v225, vcc
	v_cndmask_b32_e64 v113, v225, v113, vcc
	v_cvt_pk_bf16_f32 v14, v106, v107
	v_cvt_pk_bf16_f32 v15, v108, v109
	v_cvt_pk_bf16_f32 v16, v110, v111
	v_cvt_pk_bf16_f32 v17, v112, v113
	v_lshlrev_b32_e32 v22, 16, v14
	v_and_b32_e32 v23, 0xffff0000, v14
	v_sub_f32_e32 v106, v106, v22
	v_sub_f32_e32 v107, v107, v23
	v_cvt_pk_bf16_f32 v18, v106, v107
	v_lshlrev_b32_e32 v22, 16, v15
	v_and_b32_e32 v23, 0xffff0000, v15
	v_sub_f32_e32 v108, v108, v22
	v_sub_f32_e32 v109, v109, v23
	v_cvt_pk_bf16_f32 v19, v108, v109
	v_lshlrev_b32_e32 v22, 16, v16
	v_and_b32_e32 v23, 0xffff0000, v16
	v_sub_f32_e32 v110, v110, v22
	v_sub_f32_e32 v111, v111, v23
	v_cvt_pk_bf16_f32 v20, v110, v111
	v_lshlrev_b32_e32 v22, 16, v17
	v_and_b32_e32 v23, 0xffff0000, v17
	v_sub_f32_e32 v112, v112, v22
	v_sub_f32_e32 v113, v113, v23
	v_cvt_pk_bf16_f32 v21, v112, v113
	s_waitcnt lgkmcnt(0)
	v_mfma_f32_16x16x32_bf16 v[10:13], v[198:201], v[14:17], v[10:13]
	v_mfma_f32_16x16x32_bf16 v[6:9], v[206:209], v[14:17], v[6:9]
	v_mfma_f32_16x16x32_bf16 v[2:5], v[214:217], v[14:17], v[2:5]
	v_mfma_f32_16x16x32_bf16 v[10:13], v[198:201], v[18:21], v[10:13]
	ds_read_b128 v[198:201], v122 offset:1408
	v_mfma_f32_16x16x32_bf16 v[6:9], v[206:209], v[18:21], v[6:9]
	ds_read_b128 v[206:209], v122 offset:34432
	v_mfma_f32_16x16x32_bf16 v[2:5], v[214:217], v[18:21], v[2:5]
	ds_read_b128 v[214:217], v28 offset:1408
	v_mfma_f32_16x16x32_bf16 v[10:13], v[202:205], v[14:17], v[10:13]
	ds_read_b128 v[202:205], v123 offset:1408
	v_mfma_f32_16x16x32_bf16 v[6:9], v[210:213], v[14:17], v[6:9]
	ds_read_b128 v[210:213], v123 offset:34432
	v_mfma_f32_16x16x32_bf16 v[2:5], v[218:221], v[14:17], v[2:5]
	ds_read_b128 v[218:221], v29 offset:1408
	s_waitcnt vmcnt(36)
	v_cndmask_b32_e64 v24, v115, v114, vcc
	v_cndmask_b32_e64 v25, v117, v116, vcc
	v_cndmask_b32_e64 v26, v119, v118, vcc
	v_cndmask_b32_e64 v27, v121, v120, vcc
	v_mov_b32_dpp v222, v24 quad_perm:[1,0,3,2] row_mask:0xf bank_mask:0xf
	v_mov_b32_dpp v223, v25 quad_perm:[1,0,3,2] row_mask:0xf bank_mask:0xf
	v_mov_b32_dpp v224, v26 quad_perm:[1,0,3,2] row_mask:0xf bank_mask:0xf
	v_mov_b32_dpp v225, v27 quad_perm:[1,0,3,2] row_mask:0xf bank_mask:0xf
	v_cndmask_b32_e64 v114, v114, v222, vcc
	v_cndmask_b32_e64 v115, v222, v115, vcc
	v_cndmask_b32_e64 v116, v116, v223, vcc
	v_cndmask_b32_e64 v117, v223, v117, vcc
	v_cndmask_b32_e64 v118, v118, v224, vcc
	v_cndmask_b32_e64 v119, v224, v119, vcc
	v_cndmask_b32_e64 v120, v120, v225, vcc
	v_cndmask_b32_e64 v121, v225, v121, vcc
	v_cvt_pk_bf16_f32 v14, v114, v115
	v_cvt_pk_bf16_f32 v15, v116, v117
	v_cvt_pk_bf16_f32 v16, v118, v119
	v_cvt_pk_bf16_f32 v17, v120, v121
	v_lshlrev_b32_e32 v22, 16, v14
	v_and_b32_e32 v23, 0xffff0000, v14
	v_sub_f32_e32 v114, v114, v22
	v_sub_f32_e32 v115, v115, v23
	v_cvt_pk_bf16_f32 v18, v114, v115
	v_lshlrev_b32_e32 v22, 16, v15
	v_and_b32_e32 v23, 0xffff0000, v15
	v_sub_f32_e32 v116, v116, v22
	v_sub_f32_e32 v117, v117, v23
	v_cvt_pk_bf16_f32 v19, v116, v117
	v_lshlrev_b32_e32 v22, 16, v16
	v_and_b32_e32 v23, 0xffff0000, v16
	v_sub_f32_e32 v118, v118, v22
	v_sub_f32_e32 v119, v119, v23
	v_cvt_pk_bf16_f32 v20, v118, v119
	v_lshlrev_b32_e32 v22, 16, v17
	v_and_b32_e32 v23, 0xffff0000, v17
	v_sub_f32_e32 v120, v120, v22
	v_sub_f32_e32 v121, v121, v23
	v_cvt_pk_bf16_f32 v21, v120, v121
	s_waitcnt lgkmcnt(0)
	v_mfma_f32_16x16x32_bf16 v[10:13], v[198:201], v[14:17], v[10:13]
	v_mfma_f32_16x16x32_bf16 v[6:9], v[206:209], v[14:17], v[6:9]
	v_mfma_f32_16x16x32_bf16 v[2:5], v[214:217], v[14:17], v[2:5]
	v_mfma_f32_16x16x32_bf16 v[10:13], v[198:201], v[18:21], v[10:13]
	ds_read_b128 v[198:201], v122 offset:1472
	v_mfma_f32_16x16x32_bf16 v[6:9], v[206:209], v[18:21], v[6:9]
	ds_read_b128 v[206:209], v122 offset:34496
	v_mfma_f32_16x16x32_bf16 v[2:5], v[214:217], v[18:21], v[2:5]
	ds_read_b128 v[214:217], v28 offset:1472
	v_mfma_f32_16x16x32_bf16 v[10:13], v[202:205], v[14:17], v[10:13]
	ds_read_b128 v[202:205], v123 offset:1472
	v_mfma_f32_16x16x32_bf16 v[6:9], v[210:213], v[14:17], v[6:9]
	ds_read_b128 v[210:213], v123 offset:34496
	v_mfma_f32_16x16x32_bf16 v[2:5], v[218:221], v[14:17], v[2:5]
	ds_read_b128 v[218:221], v29 offset:1472
	s_waitcnt vmcnt(32)
	v_cndmask_b32_e64 v24, v127, v126, vcc
	v_cndmask_b32_e64 v25, v129, v128, vcc
	v_cndmask_b32_e64 v26, v131, v130, vcc
	v_cndmask_b32_e64 v27, v133, v132, vcc
	v_mov_b32_dpp v222, v24 quad_perm:[1,0,3,2] row_mask:0xf bank_mask:0xf
	v_mov_b32_dpp v223, v25 quad_perm:[1,0,3,2] row_mask:0xf bank_mask:0xf
	v_mov_b32_dpp v224, v26 quad_perm:[1,0,3,2] row_mask:0xf bank_mask:0xf
	v_mov_b32_dpp v225, v27 quad_perm:[1,0,3,2] row_mask:0xf bank_mask:0xf
	v_cndmask_b32_e64 v126, v126, v222, vcc
	v_cndmask_b32_e64 v127, v222, v127, vcc
	v_cndmask_b32_e64 v128, v128, v223, vcc
	v_cndmask_b32_e64 v129, v223, v129, vcc
	v_cndmask_b32_e64 v130, v130, v224, vcc
	v_cndmask_b32_e64 v131, v224, v131, vcc
	v_cndmask_b32_e64 v132, v132, v225, vcc
	v_cndmask_b32_e64 v133, v225, v133, vcc
	v_cvt_pk_bf16_f32 v14, v126, v127
	v_cvt_pk_bf16_f32 v15, v128, v129
	v_cvt_pk_bf16_f32 v16, v130, v131
	v_cvt_pk_bf16_f32 v17, v132, v133
	v_lshlrev_b32_e32 v22, 16, v14
	v_and_b32_e32 v23, 0xffff0000, v14
	v_sub_f32_e32 v126, v126, v22
	v_sub_f32_e32 v127, v127, v23
	v_cvt_pk_bf16_f32 v18, v126, v127
	v_lshlrev_b32_e32 v22, 16, v15
	v_and_b32_e32 v23, 0xffff0000, v15
	v_sub_f32_e32 v128, v128, v22
	v_sub_f32_e32 v129, v129, v23
	v_cvt_pk_bf16_f32 v19, v128, v129
	v_lshlrev_b32_e32 v22, 16, v16
	v_and_b32_e32 v23, 0xffff0000, v16
	v_sub_f32_e32 v130, v130, v22
	v_sub_f32_e32 v131, v131, v23
	v_cvt_pk_bf16_f32 v20, v130, v131
	v_lshlrev_b32_e32 v22, 16, v17
	v_and_b32_e32 v23, 0xffff0000, v17
	v_sub_f32_e32 v132, v132, v22
	v_sub_f32_e32 v133, v133, v23
	v_cvt_pk_bf16_f32 v21, v132, v133
	s_waitcnt lgkmcnt(0)
	v_mfma_f32_16x16x32_bf16 v[10:13], v[198:201], v[14:17], v[10:13]
	v_mfma_f32_16x16x32_bf16 v[6:9], v[206:209], v[14:17], v[6:9]
	v_mfma_f32_16x16x32_bf16 v[2:5], v[214:217], v[14:17], v[2:5]
	v_mfma_f32_16x16x32_bf16 v[10:13], v[198:201], v[18:21], v[10:13]
	ds_read_b128 v[198:201], v122 offset:1536
	v_mfma_f32_16x16x32_bf16 v[6:9], v[206:209], v[18:21], v[6:9]
	ds_read_b128 v[206:209], v122 offset:34560
	v_mfma_f32_16x16x32_bf16 v[2:5], v[214:217], v[18:21], v[2:5]
	ds_read_b128 v[214:217], v28 offset:1536
	v_mfma_f32_16x16x32_bf16 v[10:13], v[202:205], v[14:17], v[10:13]
	ds_read_b128 v[202:205], v123 offset:1536
	v_mfma_f32_16x16x32_bf16 v[6:9], v[210:213], v[14:17], v[6:9]
	ds_read_b128 v[210:213], v123 offset:34560
	v_mfma_f32_16x16x32_bf16 v[2:5], v[218:221], v[14:17], v[2:5]
	ds_read_b128 v[218:221], v29 offset:1536
	s_waitcnt vmcnt(28)
	v_cndmask_b32_e64 v24, v135, v134, vcc
	v_cndmask_b32_e64 v25, v137, v136, vcc
	v_cndmask_b32_e64 v26, v139, v138, vcc
	v_cndmask_b32_e64 v27, v141, v140, vcc
	v_mov_b32_dpp v222, v24 quad_perm:[1,0,3,2] row_mask:0xf bank_mask:0xf
	v_mov_b32_dpp v223, v25 quad_perm:[1,0,3,2] row_mask:0xf bank_mask:0xf
	v_mov_b32_dpp v224, v26 quad_perm:[1,0,3,2] row_mask:0xf bank_mask:0xf
	v_mov_b32_dpp v225, v27 quad_perm:[1,0,3,2] row_mask:0xf bank_mask:0xf
	v_cndmask_b32_e64 v134, v134, v222, vcc
	v_cndmask_b32_e64 v135, v222, v135, vcc
	v_cndmask_b32_e64 v136, v136, v223, vcc
	v_cndmask_b32_e64 v137, v223, v137, vcc
	v_cndmask_b32_e64 v138, v138, v224, vcc
	v_cndmask_b32_e64 v139, v224, v139, vcc
	v_cndmask_b32_e64 v140, v140, v225, vcc
	v_cndmask_b32_e64 v141, v225, v141, vcc
	v_cvt_pk_bf16_f32 v14, v134, v135
	v_cvt_pk_bf16_f32 v15, v136, v137
	v_cvt_pk_bf16_f32 v16, v138, v139
	v_cvt_pk_bf16_f32 v17, v140, v141
	v_lshlrev_b32_e32 v22, 16, v14
	v_and_b32_e32 v23, 0xffff0000, v14
	v_sub_f32_e32 v134, v134, v22
	v_sub_f32_e32 v135, v135, v23
	v_cvt_pk_bf16_f32 v18, v134, v135
	v_lshlrev_b32_e32 v22, 16, v15
	v_and_b32_e32 v23, 0xffff0000, v15
	v_sub_f32_e32 v136, v136, v22
	v_sub_f32_e32 v137, v137, v23
	v_cvt_pk_bf16_f32 v19, v136, v137
	v_lshlrev_b32_e32 v22, 16, v16
	v_and_b32_e32 v23, 0xffff0000, v16
	v_sub_f32_e32 v138, v138, v22
	v_sub_f32_e32 v139, v139, v23
	v_cvt_pk_bf16_f32 v20, v138, v139
	v_lshlrev_b32_e32 v22, 16, v17
	v_and_b32_e32 v23, 0xffff0000, v17
	v_sub_f32_e32 v140, v140, v22
	v_sub_f32_e32 v141, v141, v23
	v_cvt_pk_bf16_f32 v21, v140, v141
	s_waitcnt lgkmcnt(0)
	v_mfma_f32_16x16x32_bf16 v[10:13], v[198:201], v[14:17], v[10:13]
	v_mfma_f32_16x16x32_bf16 v[6:9], v[206:209], v[14:17], v[6:9]
	v_mfma_f32_16x16x32_bf16 v[2:5], v[214:217], v[14:17], v[2:5]
	v_mfma_f32_16x16x32_bf16 v[10:13], v[198:201], v[18:21], v[10:13]
	ds_read_b128 v[198:201], v122 offset:1600
	v_mfma_f32_16x16x32_bf16 v[6:9], v[206:209], v[18:21], v[6:9]
	ds_read_b128 v[206:209], v122 offset:34624
	v_mfma_f32_16x16x32_bf16 v[2:5], v[214:217], v[18:21], v[2:5]
	ds_read_b128 v[214:217], v28 offset:1600
	v_mfma_f32_16x16x32_bf16 v[10:13], v[202:205], v[14:17], v[10:13]
	ds_read_b128 v[202:205], v123 offset:1600
	v_mfma_f32_16x16x32_bf16 v[6:9], v[210:213], v[14:17], v[6:9]
	ds_read_b128 v[210:213], v123 offset:34624
	v_mfma_f32_16x16x32_bf16 v[2:5], v[218:221], v[14:17], v[2:5]
	ds_read_b128 v[218:221], v29 offset:1600
	s_waitcnt vmcnt(24)
	v_cndmask_b32_e64 v24, v143, v142, vcc
	v_cndmask_b32_e64 v25, v145, v144, vcc
	v_cndmask_b32_e64 v26, v147, v146, vcc
	v_cndmask_b32_e64 v27, v149, v148, vcc
	v_mov_b32_dpp v222, v24 quad_perm:[1,0,3,2] row_mask:0xf bank_mask:0xf
	v_mov_b32_dpp v223, v25 quad_perm:[1,0,3,2] row_mask:0xf bank_mask:0xf
	v_mov_b32_dpp v224, v26 quad_perm:[1,0,3,2] row_mask:0xf bank_mask:0xf
	v_mov_b32_dpp v225, v27 quad_perm:[1,0,3,2] row_mask:0xf bank_mask:0xf
	v_cndmask_b32_e64 v142, v142, v222, vcc
	v_cndmask_b32_e64 v143, v222, v143, vcc
	v_cndmask_b32_e64 v144, v144, v223, vcc
	v_cndmask_b32_e64 v145, v223, v145, vcc
	v_cndmask_b32_e64 v146, v146, v224, vcc
	v_cndmask_b32_e64 v147, v224, v147, vcc
	v_cndmask_b32_e64 v148, v148, v225, vcc
	v_cndmask_b32_e64 v149, v225, v149, vcc
	v_cvt_pk_bf16_f32 v14, v142, v143
	v_cvt_pk_bf16_f32 v15, v144, v145
	v_cvt_pk_bf16_f32 v16, v146, v147
	v_cvt_pk_bf16_f32 v17, v148, v149
	v_lshlrev_b32_e32 v22, 16, v14
	v_and_b32_e32 v23, 0xffff0000, v14
	v_sub_f32_e32 v142, v142, v22
	v_sub_f32_e32 v143, v143, v23
	v_cvt_pk_bf16_f32 v18, v142, v143
	v_lshlrev_b32_e32 v22, 16, v15
	v_and_b32_e32 v23, 0xffff0000, v15
	v_sub_f32_e32 v144, v144, v22
	v_sub_f32_e32 v145, v145, v23
	v_cvt_pk_bf16_f32 v19, v144, v145
	v_lshlrev_b32_e32 v22, 16, v16
	v_and_b32_e32 v23, 0xffff0000, v16
	v_sub_f32_e32 v146, v146, v22
	v_sub_f32_e32 v147, v147, v23
	v_cvt_pk_bf16_f32 v20, v146, v147
	v_lshlrev_b32_e32 v22, 16, v17
	v_and_b32_e32 v23, 0xffff0000, v17
	v_sub_f32_e32 v148, v148, v22
	v_sub_f32_e32 v149, v149, v23
	v_cvt_pk_bf16_f32 v21, v148, v149
	s_waitcnt lgkmcnt(0)
	v_mfma_f32_16x16x32_bf16 v[10:13], v[198:201], v[14:17], v[10:13]
	v_mfma_f32_16x16x32_bf16 v[6:9], v[206:209], v[14:17], v[6:9]
	v_mfma_f32_16x16x32_bf16 v[2:5], v[214:217], v[14:17], v[2:5]
	v_mfma_f32_16x16x32_bf16 v[10:13], v[198:201], v[18:21], v[10:13]
	ds_read_b128 v[198:201], v122 offset:1664
	v_mfma_f32_16x16x32_bf16 v[6:9], v[206:209], v[18:21], v[6:9]
	ds_read_b128 v[206:209], v122 offset:34688
	v_mfma_f32_16x16x32_bf16 v[2:5], v[214:217], v[18:21], v[2:5]
	ds_read_b128 v[214:217], v28 offset:1664
	v_mfma_f32_16x16x32_bf16 v[10:13], v[202:205], v[14:17], v[10:13]
	ds_read_b128 v[202:205], v123 offset:1664
	v_mfma_f32_16x16x32_bf16 v[6:9], v[210:213], v[14:17], v[6:9]
	ds_read_b128 v[210:213], v123 offset:34688
	v_mfma_f32_16x16x32_bf16 v[2:5], v[218:221], v[14:17], v[2:5]
	ds_read_b128 v[218:221], v29 offset:1664
	s_waitcnt vmcnt(20)
	v_cndmask_b32_e64 v24, v151, v150, vcc
	v_cndmask_b32_e64 v25, v153, v152, vcc
	v_cndmask_b32_e64 v26, v155, v154, vcc
	v_cndmask_b32_e64 v27, v157, v156, vcc
	v_mov_b32_dpp v222, v24 quad_perm:[1,0,3,2] row_mask:0xf bank_mask:0xf
	v_mov_b32_dpp v223, v25 quad_perm:[1,0,3,2] row_mask:0xf bank_mask:0xf
	v_mov_b32_dpp v224, v26 quad_perm:[1,0,3,2] row_mask:0xf bank_mask:0xf
	v_mov_b32_dpp v225, v27 quad_perm:[1,0,3,2] row_mask:0xf bank_mask:0xf
	v_cndmask_b32_e64 v150, v150, v222, vcc
	v_cndmask_b32_e64 v151, v222, v151, vcc
	v_cndmask_b32_e64 v152, v152, v223, vcc
	v_cndmask_b32_e64 v153, v223, v153, vcc
	v_cndmask_b32_e64 v154, v154, v224, vcc
	v_cndmask_b32_e64 v155, v224, v155, vcc
	v_cndmask_b32_e64 v156, v156, v225, vcc
	v_cndmask_b32_e64 v157, v225, v157, vcc
	v_cvt_pk_bf16_f32 v14, v150, v151
	v_cvt_pk_bf16_f32 v15, v152, v153
	v_cvt_pk_bf16_f32 v16, v154, v155
	v_cvt_pk_bf16_f32 v17, v156, v157
	v_lshlrev_b32_e32 v22, 16, v14
	v_and_b32_e32 v23, 0xffff0000, v14
	v_sub_f32_e32 v150, v150, v22
	v_sub_f32_e32 v151, v151, v23
	v_cvt_pk_bf16_f32 v18, v150, v151
	v_lshlrev_b32_e32 v22, 16, v15
	v_and_b32_e32 v23, 0xffff0000, v15
	v_sub_f32_e32 v152, v152, v22
	v_sub_f32_e32 v153, v153, v23
	v_cvt_pk_bf16_f32 v19, v152, v153
	v_lshlrev_b32_e32 v22, 16, v16
	v_and_b32_e32 v23, 0xffff0000, v16
	v_sub_f32_e32 v154, v154, v22
	v_sub_f32_e32 v155, v155, v23
	v_cvt_pk_bf16_f32 v20, v154, v155
	v_lshlrev_b32_e32 v22, 16, v17
	v_and_b32_e32 v23, 0xffff0000, v17
	v_sub_f32_e32 v156, v156, v22
	v_sub_f32_e32 v157, v157, v23
	v_cvt_pk_bf16_f32 v21, v156, v157
	s_waitcnt lgkmcnt(0)
	v_mfma_f32_16x16x32_bf16 v[10:13], v[198:201], v[14:17], v[10:13]
	v_mfma_f32_16x16x32_bf16 v[6:9], v[206:209], v[14:17], v[6:9]
	v_mfma_f32_16x16x32_bf16 v[2:5], v[214:217], v[14:17], v[2:5]
	v_mfma_f32_16x16x32_bf16 v[10:13], v[198:201], v[18:21], v[10:13]
	ds_read_b128 v[198:201], v122 offset:1728
	v_mfma_f32_16x16x32_bf16 v[6:9], v[206:209], v[18:21], v[6:9]
	ds_read_b128 v[206:209], v122 offset:34752
	v_mfma_f32_16x16x32_bf16 v[2:5], v[214:217], v[18:21], v[2:5]
	ds_read_b128 v[214:217], v28 offset:1728
	v_mfma_f32_16x16x32_bf16 v[10:13], v[202:205], v[14:17], v[10:13]
	ds_read_b128 v[202:205], v123 offset:1728
	v_mfma_f32_16x16x32_bf16 v[6:9], v[210:213], v[14:17], v[6:9]
	ds_read_b128 v[210:213], v123 offset:34752
	v_mfma_f32_16x16x32_bf16 v[2:5], v[218:221], v[14:17], v[2:5]
	ds_read_b128 v[218:221], v29 offset:1728
	s_waitcnt vmcnt(16)
	v_cndmask_b32_e64 v24, v159, v158, vcc
	v_cndmask_b32_e64 v25, v161, v160, vcc
	v_cndmask_b32_e64 v26, v163, v162, vcc
	v_cndmask_b32_e64 v27, v165, v164, vcc
	v_mov_b32_dpp v222, v24 quad_perm:[1,0,3,2] row_mask:0xf bank_mask:0xf
	v_mov_b32_dpp v223, v25 quad_perm:[1,0,3,2] row_mask:0xf bank_mask:0xf
	v_mov_b32_dpp v224, v26 quad_perm:[1,0,3,2] row_mask:0xf bank_mask:0xf
	v_mov_b32_dpp v225, v27 quad_perm:[1,0,3,2] row_mask:0xf bank_mask:0xf
	v_cndmask_b32_e64 v158, v158, v222, vcc
	v_cndmask_b32_e64 v159, v222, v159, vcc
	v_cndmask_b32_e64 v160, v160, v223, vcc
	v_cndmask_b32_e64 v161, v223, v161, vcc
	v_cndmask_b32_e64 v162, v162, v224, vcc
	v_cndmask_b32_e64 v163, v224, v163, vcc
	v_cndmask_b32_e64 v164, v164, v225, vcc
	v_cndmask_b32_e64 v165, v225, v165, vcc
	v_cvt_pk_bf16_f32 v14, v158, v159
	v_cvt_pk_bf16_f32 v15, v160, v161
	v_cvt_pk_bf16_f32 v16, v162, v163
	v_cvt_pk_bf16_f32 v17, v164, v165
	v_lshlrev_b32_e32 v22, 16, v14
	v_and_b32_e32 v23, 0xffff0000, v14
	v_sub_f32_e32 v158, v158, v22
	v_sub_f32_e32 v159, v159, v23
	v_cvt_pk_bf16_f32 v18, v158, v159
	v_lshlrev_b32_e32 v22, 16, v15
	v_and_b32_e32 v23, 0xffff0000, v15
	v_sub_f32_e32 v160, v160, v22
	v_sub_f32_e32 v161, v161, v23
	v_cvt_pk_bf16_f32 v19, v160, v161
	v_lshlrev_b32_e32 v22, 16, v16
	v_and_b32_e32 v23, 0xffff0000, v16
	v_sub_f32_e32 v162, v162, v22
	v_sub_f32_e32 v163, v163, v23
	v_cvt_pk_bf16_f32 v20, v162, v163
	v_lshlrev_b32_e32 v22, 16, v17
	v_and_b32_e32 v23, 0xffff0000, v17
	v_sub_f32_e32 v164, v164, v22
	v_sub_f32_e32 v165, v165, v23
	v_cvt_pk_bf16_f32 v21, v164, v165
	s_waitcnt lgkmcnt(0)
	v_mfma_f32_16x16x32_bf16 v[10:13], v[198:201], v[14:17], v[10:13]
	v_mfma_f32_16x16x32_bf16 v[6:9], v[206:209], v[14:17], v[6:9]
	v_mfma_f32_16x16x32_bf16 v[2:5], v[214:217], v[14:17], v[2:5]
	v_mfma_f32_16x16x32_bf16 v[10:13], v[198:201], v[18:21], v[10:13]
	ds_read_b128 v[198:201], v122 offset:1792
	v_mfma_f32_16x16x32_bf16 v[6:9], v[206:209], v[18:21], v[6:9]
	ds_read_b128 v[206:209], v122 offset:34816
	v_mfma_f32_16x16x32_bf16 v[2:5], v[214:217], v[18:21], v[2:5]
	ds_read_b128 v[214:217], v28 offset:1792
	v_mfma_f32_16x16x32_bf16 v[10:13], v[202:205], v[14:17], v[10:13]
	ds_read_b128 v[202:205], v123 offset:1792
	v_mfma_f32_16x16x32_bf16 v[6:9], v[210:213], v[14:17], v[6:9]
	ds_read_b128 v[210:213], v123 offset:34816
	v_mfma_f32_16x16x32_bf16 v[2:5], v[218:221], v[14:17], v[2:5]
	ds_read_b128 v[218:221], v29 offset:1792
	s_waitcnt vmcnt(12)
	v_cndmask_b32_e64 v24, v167, v166, vcc
	v_cndmask_b32_e64 v25, v169, v168, vcc
	v_cndmask_b32_e64 v26, v171, v170, vcc
	v_cndmask_b32_e64 v27, v173, v172, vcc
	v_mov_b32_dpp v222, v24 quad_perm:[1,0,3,2] row_mask:0xf bank_mask:0xf
	v_mov_b32_dpp v223, v25 quad_perm:[1,0,3,2] row_mask:0xf bank_mask:0xf
	v_mov_b32_dpp v224, v26 quad_perm:[1,0,3,2] row_mask:0xf bank_mask:0xf
	v_mov_b32_dpp v225, v27 quad_perm:[1,0,3,2] row_mask:0xf bank_mask:0xf
	v_cndmask_b32_e64 v166, v166, v222, vcc
	v_cndmask_b32_e64 v167, v222, v167, vcc
	v_cndmask_b32_e64 v168, v168, v223, vcc
	v_cndmask_b32_e64 v169, v223, v169, vcc
	v_cndmask_b32_e64 v170, v170, v224, vcc
	v_cndmask_b32_e64 v171, v224, v171, vcc
	v_cndmask_b32_e64 v172, v172, v225, vcc
	v_cndmask_b32_e64 v173, v225, v173, vcc
	v_cvt_pk_bf16_f32 v14, v166, v167
	v_cvt_pk_bf16_f32 v15, v168, v169
	v_cvt_pk_bf16_f32 v16, v170, v171
	v_cvt_pk_bf16_f32 v17, v172, v173
	v_lshlrev_b32_e32 v22, 16, v14
	v_and_b32_e32 v23, 0xffff0000, v14
	v_sub_f32_e32 v166, v166, v22
	v_sub_f32_e32 v167, v167, v23
	v_cvt_pk_bf16_f32 v18, v166, v167
	v_lshlrev_b32_e32 v22, 16, v15
	v_and_b32_e32 v23, 0xffff0000, v15
	v_sub_f32_e32 v168, v168, v22
	v_sub_f32_e32 v169, v169, v23
	v_cvt_pk_bf16_f32 v19, v168, v169
	v_lshlrev_b32_e32 v22, 16, v16
	v_and_b32_e32 v23, 0xffff0000, v16
	v_sub_f32_e32 v170, v170, v22
	v_sub_f32_e32 v171, v171, v23
	v_cvt_pk_bf16_f32 v20, v170, v171
	v_lshlrev_b32_e32 v22, 16, v17
	v_and_b32_e32 v23, 0xffff0000, v17
	v_sub_f32_e32 v172, v172, v22
	v_sub_f32_e32 v173, v173, v23
	v_cvt_pk_bf16_f32 v21, v172, v173
	s_waitcnt lgkmcnt(0)
	v_mfma_f32_16x16x32_bf16 v[10:13], v[198:201], v[14:17], v[10:13]
	v_mfma_f32_16x16x32_bf16 v[6:9], v[206:209], v[14:17], v[6:9]
	v_mfma_f32_16x16x32_bf16 v[2:5], v[214:217], v[14:17], v[2:5]
	v_mfma_f32_16x16x32_bf16 v[10:13], v[198:201], v[18:21], v[10:13]
	ds_read_b128 v[198:201], v122 offset:1856
	v_mfma_f32_16x16x32_bf16 v[6:9], v[206:209], v[18:21], v[6:9]
	ds_read_b128 v[206:209], v122 offset:34880
	v_mfma_f32_16x16x32_bf16 v[2:5], v[214:217], v[18:21], v[2:5]
	ds_read_b128 v[214:217], v28 offset:1856
	v_mfma_f32_16x16x32_bf16 v[10:13], v[202:205], v[14:17], v[10:13]
	ds_read_b128 v[202:205], v123 offset:1856
	v_mfma_f32_16x16x32_bf16 v[6:9], v[210:213], v[14:17], v[6:9]
	ds_read_b128 v[210:213], v123 offset:34880
	v_mfma_f32_16x16x32_bf16 v[2:5], v[218:221], v[14:17], v[2:5]
	ds_read_b128 v[218:221], v29 offset:1856
	s_waitcnt vmcnt(8)
	v_cndmask_b32_e64 v24, v175, v174, vcc
	v_cndmask_b32_e64 v25, v177, v176, vcc
	v_cndmask_b32_e64 v26, v179, v178, vcc
	v_cndmask_b32_e64 v27, v181, v180, vcc
	v_mov_b32_dpp v222, v24 quad_perm:[1,0,3,2] row_mask:0xf bank_mask:0xf
	v_mov_b32_dpp v223, v25 quad_perm:[1,0,3,2] row_mask:0xf bank_mask:0xf
	v_mov_b32_dpp v224, v26 quad_perm:[1,0,3,2] row_mask:0xf bank_mask:0xf
	v_mov_b32_dpp v225, v27 quad_perm:[1,0,3,2] row_mask:0xf bank_mask:0xf
	v_cndmask_b32_e64 v174, v174, v222, vcc
	v_cndmask_b32_e64 v175, v222, v175, vcc
	v_cndmask_b32_e64 v176, v176, v223, vcc
	v_cndmask_b32_e64 v177, v223, v177, vcc
	v_cndmask_b32_e64 v178, v178, v224, vcc
	v_cndmask_b32_e64 v179, v224, v179, vcc
	v_cndmask_b32_e64 v180, v180, v225, vcc
	v_cndmask_b32_e64 v181, v225, v181, vcc
	v_cvt_pk_bf16_f32 v14, v174, v175
	v_cvt_pk_bf16_f32 v15, v176, v177
	v_cvt_pk_bf16_f32 v16, v178, v179
	v_cvt_pk_bf16_f32 v17, v180, v181
	v_lshlrev_b32_e32 v22, 16, v14
	v_and_b32_e32 v23, 0xffff0000, v14
	v_sub_f32_e32 v174, v174, v22
	v_sub_f32_e32 v175, v175, v23
	v_cvt_pk_bf16_f32 v18, v174, v175
	v_lshlrev_b32_e32 v22, 16, v15
	v_and_b32_e32 v23, 0xffff0000, v15
	v_sub_f32_e32 v176, v176, v22
	v_sub_f32_e32 v177, v177, v23
	v_cvt_pk_bf16_f32 v19, v176, v177
	v_lshlrev_b32_e32 v22, 16, v16
	v_and_b32_e32 v23, 0xffff0000, v16
	v_sub_f32_e32 v178, v178, v22
	v_sub_f32_e32 v179, v179, v23
	v_cvt_pk_bf16_f32 v20, v178, v179
	v_lshlrev_b32_e32 v22, 16, v17
	v_and_b32_e32 v23, 0xffff0000, v17
	v_sub_f32_e32 v180, v180, v22
	v_sub_f32_e32 v181, v181, v23
	v_cvt_pk_bf16_f32 v21, v180, v181
	s_waitcnt lgkmcnt(0)
	v_mfma_f32_16x16x32_bf16 v[10:13], v[198:201], v[14:17], v[10:13]
	v_mfma_f32_16x16x32_bf16 v[6:9], v[206:209], v[14:17], v[6:9]
	v_mfma_f32_16x16x32_bf16 v[2:5], v[214:217], v[14:17], v[2:5]
	v_mfma_f32_16x16x32_bf16 v[10:13], v[198:201], v[18:21], v[10:13]
	ds_read_b128 v[198:201], v122 offset:1920
	v_mfma_f32_16x16x32_bf16 v[6:9], v[206:209], v[18:21], v[6:9]
	ds_read_b128 v[206:209], v122 offset:34944
	v_mfma_f32_16x16x32_bf16 v[2:5], v[214:217], v[18:21], v[2:5]
	ds_read_b128 v[214:217], v28 offset:1920
	v_mfma_f32_16x16x32_bf16 v[10:13], v[202:205], v[14:17], v[10:13]
	ds_read_b128 v[202:205], v123 offset:1920
	v_mfma_f32_16x16x32_bf16 v[6:9], v[210:213], v[14:17], v[6:9]
	ds_read_b128 v[210:213], v123 offset:34944
	v_mfma_f32_16x16x32_bf16 v[2:5], v[218:221], v[14:17], v[2:5]
	ds_read_b128 v[218:221], v29 offset:1920
	s_waitcnt vmcnt(4)
	v_cndmask_b32_e64 v24, v183, v182, vcc
	v_cndmask_b32_e64 v25, v185, v184, vcc
	v_cndmask_b32_e64 v26, v187, v186, vcc
	v_cndmask_b32_e64 v27, v189, v188, vcc
	v_mov_b32_dpp v222, v24 quad_perm:[1,0,3,2] row_mask:0xf bank_mask:0xf
	v_mov_b32_dpp v223, v25 quad_perm:[1,0,3,2] row_mask:0xf bank_mask:0xf
	v_mov_b32_dpp v224, v26 quad_perm:[1,0,3,2] row_mask:0xf bank_mask:0xf
	v_mov_b32_dpp v225, v27 quad_perm:[1,0,3,2] row_mask:0xf bank_mask:0xf
	v_cndmask_b32_e64 v182, v182, v222, vcc
	v_cndmask_b32_e64 v183, v222, v183, vcc
	v_cndmask_b32_e64 v184, v184, v223, vcc
	v_cndmask_b32_e64 v185, v223, v185, vcc
	v_cndmask_b32_e64 v186, v186, v224, vcc
	v_cndmask_b32_e64 v187, v224, v187, vcc
	v_cndmask_b32_e64 v188, v188, v225, vcc
	v_cndmask_b32_e64 v189, v225, v189, vcc
	v_cvt_pk_bf16_f32 v14, v182, v183
	v_cvt_pk_bf16_f32 v15, v184, v185
	v_cvt_pk_bf16_f32 v16, v186, v187
	v_cvt_pk_bf16_f32 v17, v188, v189
	v_lshlrev_b32_e32 v22, 16, v14
	v_and_b32_e32 v23, 0xffff0000, v14
	v_sub_f32_e32 v182, v182, v22
	v_sub_f32_e32 v183, v183, v23
	v_cvt_pk_bf16_f32 v18, v182, v183
	v_lshlrev_b32_e32 v22, 16, v15
	v_and_b32_e32 v23, 0xffff0000, v15
	v_sub_f32_e32 v184, v184, v22
	v_sub_f32_e32 v185, v185, v23
	v_cvt_pk_bf16_f32 v19, v184, v185
	v_lshlrev_b32_e32 v22, 16, v16
	v_and_b32_e32 v23, 0xffff0000, v16
	v_sub_f32_e32 v186, v186, v22
	v_sub_f32_e32 v187, v187, v23
	v_cvt_pk_bf16_f32 v20, v186, v187
	v_lshlrev_b32_e32 v22, 16, v17
	v_and_b32_e32 v23, 0xffff0000, v17
	v_sub_f32_e32 v188, v188, v22
	v_sub_f32_e32 v189, v189, v23
	v_cvt_pk_bf16_f32 v21, v188, v189
	s_waitcnt lgkmcnt(0)
	v_mfma_f32_16x16x32_bf16 v[10:13], v[198:201], v[14:17], v[10:13]
	v_mfma_f32_16x16x32_bf16 v[6:9], v[206:209], v[14:17], v[6:9]
	v_mfma_f32_16x16x32_bf16 v[2:5], v[214:217], v[14:17], v[2:5]
	v_mfma_f32_16x16x32_bf16 v[10:13], v[198:201], v[18:21], v[10:13]
	ds_read_b128 v[198:201], v122 offset:1984
	v_mfma_f32_16x16x32_bf16 v[6:9], v[206:209], v[18:21], v[6:9]
	ds_read_b128 v[206:209], v122 offset:35008
	v_mfma_f32_16x16x32_bf16 v[2:5], v[214:217], v[18:21], v[2:5]
	ds_read_b128 v[214:217], v28 offset:1984
	v_mfma_f32_16x16x32_bf16 v[10:13], v[202:205], v[14:17], v[10:13]
	ds_read_b128 v[202:205], v123 offset:1984
	v_mfma_f32_16x16x32_bf16 v[6:9], v[210:213], v[14:17], v[6:9]
	ds_read_b128 v[210:213], v123 offset:35008
	v_mfma_f32_16x16x32_bf16 v[2:5], v[218:221], v[14:17], v[2:5]
	ds_read_b128 v[218:221], v29 offset:1984
	s_waitcnt vmcnt(0)
	v_cndmask_b32_e64 v24, v191, v190, vcc
	v_cndmask_b32_e64 v25, v193, v192, vcc
	v_cndmask_b32_e64 v26, v195, v194, vcc
	v_cndmask_b32_e64 v27, v197, v196, vcc
	v_mov_b32_dpp v222, v24 quad_perm:[1,0,3,2] row_mask:0xf bank_mask:0xf
	v_mov_b32_dpp v223, v25 quad_perm:[1,0,3,2] row_mask:0xf bank_mask:0xf
	v_mov_b32_dpp v224, v26 quad_perm:[1,0,3,2] row_mask:0xf bank_mask:0xf
	v_mov_b32_dpp v225, v27 quad_perm:[1,0,3,2] row_mask:0xf bank_mask:0xf
	v_cndmask_b32_e64 v190, v190, v222, vcc
	v_cndmask_b32_e64 v191, v222, v191, vcc
	v_cndmask_b32_e64 v192, v192, v223, vcc
	v_cndmask_b32_e64 v193, v223, v193, vcc
	v_cndmask_b32_e64 v194, v194, v224, vcc
	v_cndmask_b32_e64 v195, v224, v195, vcc
	v_cndmask_b32_e64 v196, v196, v225, vcc
	v_cndmask_b32_e64 v197, v225, v197, vcc
	v_cvt_pk_bf16_f32 v14, v190, v191
	v_cvt_pk_bf16_f32 v15, v192, v193
	v_cvt_pk_bf16_f32 v16, v194, v195
	v_cvt_pk_bf16_f32 v17, v196, v197
	v_lshlrev_b32_e32 v22, 16, v14
	v_and_b32_e32 v23, 0xffff0000, v14
	v_sub_f32_e32 v190, v190, v22
	v_sub_f32_e32 v191, v191, v23
	v_cvt_pk_bf16_f32 v18, v190, v191
	v_lshlrev_b32_e32 v22, 16, v15
	v_and_b32_e32 v23, 0xffff0000, v15
	v_sub_f32_e32 v192, v192, v22
	v_sub_f32_e32 v193, v193, v23
	v_cvt_pk_bf16_f32 v19, v192, v193
	v_lshlrev_b32_e32 v22, 16, v16
	v_and_b32_e32 v23, 0xffff0000, v16
	v_sub_f32_e32 v194, v194, v22
	v_sub_f32_e32 v195, v195, v23
	v_cvt_pk_bf16_f32 v20, v194, v195
	v_lshlrev_b32_e32 v22, 16, v17
	v_and_b32_e32 v23, 0xffff0000, v17
	v_sub_f32_e32 v196, v196, v22
	v_sub_f32_e32 v197, v197, v23
	v_cvt_pk_bf16_f32 v21, v196, v197
	s_waitcnt lgkmcnt(0)
	v_mfma_f32_16x16x32_bf16 v[10:13], v[198:201], v[14:17], v[10:13]
	v_mfma_f32_16x16x32_bf16 v[6:9], v[206:209], v[14:17], v[6:9]
	v_mfma_f32_16x16x32_bf16 v[2:5], v[214:217], v[14:17], v[2:5]
	v_mfma_f32_16x16x32_bf16 v[10:13], v[198:201], v[18:21], v[10:13]
	v_mfma_f32_16x16x32_bf16 v[6:9], v[206:209], v[18:21], v[6:9]
	v_mfma_f32_16x16x32_bf16 v[2:5], v[214:217], v[18:21], v[2:5]
	v_mfma_f32_16x16x32_bf16 v[10:13], v[202:205], v[14:17], v[10:13]
	v_mfma_f32_16x16x32_bf16 v[6:9], v[210:213], v[14:17], v[6:9]
	v_mfma_f32_16x16x32_bf16 v[2:5], v[218:221], v[14:17], v[2:5]
	s_nop 7
	s_nop 3
	s_and_b64 vcc, exec, s[46:47]
	s_cbranch_vccz .LBB0_50
	s_mul_i32 vcc_lo, s40, 0x1800
	s_ashr_i32 vcc_hi, vcc_lo, 31
	s_lshl_b64 vcc, vcc, 2
	s_add_u32 vcc_lo, s38, vcc_lo
	v_or_b32_e32 v14, s50, v32
	s_addc_u32 vcc_hi, s39, vcc_hi
	v_ashrrev_i32_e32 v15, 31, v14
	v_lshl_add_u64 v[14:15], v[14:15], 2, vcc
	global_load_dword v16, v[14:15], off
	s_branch .LBB0_51
